# U-sweep loop rewritten by hand: back-to-back fp8 MFMAs, SGPR-base loads, permlane row sum, exec-masked store
# speedup vs baseline: 1.0112x; 1.0112x over previous
.LBB0_88:
	s_andn2_saveexec_b64 s[0:1], s[0:1]
	v_mov_b32_e32 v22, s53
	v_add_f32_e32 v22, s49, v22
	v_add_f32_e32 v34, s52, v22
	s_or_b64 exec, exec, s[0:1]
	v_add_u32_e32 v35, 0x3000, v21
	v_max_f32_e64 v21, s48, s48
	v_max_f32_e64 v22, s44, s44
	v_max_f32_e32 v21, v22, v21
	v_max_f32_e64 v22, s45, s45
	v_max_f32_e64 v23, s95, s95
	v_max_f32_e32 v22, v23, v22
	s_mov_b32 s12, 0x1e3ce508
	v_max3_f32 v21, v21, v22, s12
	s_mov_b32 s13, 0x43700000
	v_div_scale_f32 v22, s[0:1], v21, v21, s13
	v_rcp_f32_e32 v23, v22
	v_readlane_b32 s0, v254, 10
	v_add_u32_e32 v20, 0x3000, v20
	v_readlane_b32 s1, v254, 11
	v_fma_f32 v55, -v22, v23, 1.0
	v_fmac_f32_e32 v23, v55, v23
	v_div_scale_f32 v55, vcc, s13, v21, s13
	v_mul_f32_e32 v128, v55, v23
	v_fma_f32 v187, -v22, v128, v55
	v_fmac_f32_e32 v128, v187, v23
	v_fma_f32 v22, -v22, v128, v55
	v_div_fmas_f32 v22, v22, v23, v128
	v_div_fixup_f32 v22, v22, v21, s13
	v_mul_f32_e32 v128, 0x3b888889, v21
	v_mul_f32_e32 v21, v22, v94
	v_mul_f32_e32 v23, v22, v186
	v_mov_b32_e32 v94, v155
	v_cvt_pk_fp8_f32 v94, v21, v23
	v_mul_f32_e32 v21, v22, v184
	v_mul_f32_e32 v23, v22, v185
	v_cmp_ne_u32_e32 vcc, -1, v20
	v_cvt_pk_fp8_f32 v94, v21, v23 op_sel:[0,0,1]
	v_mul_f32_e32 v21, v22, v95
	v_mul_f32_e32 v23, v22, v175
	v_mov_b32_e32 v95, v155
	v_cvt_pk_fp8_f32 v95, v21, v23
	v_mul_f32_e32 v21, v22, v173
	v_mul_f32_e32 v23, v22, v174
	v_max_f32_e64 v55, s60, s60
	v_cvt_pk_fp8_f32 v95, v21, v23 op_sel:[0,0,1]
	v_mul_f32_e32 v21, v22, v96
	v_mul_f32_e32 v23, v22, v170
	v_mov_b32_e32 v96, v155
	v_cvt_pk_fp8_f32 v96, v21, v23
	v_mul_f32_e32 v21, v22, v171
	v_mul_f32_e32 v23, v22, v172
	s_mov_b32 s95, 0
	v_cvt_pk_fp8_f32 v96, v21, v23 op_sel:[0,0,1]
	v_mul_f32_e32 v21, v22, v97
	v_mul_f32_e32 v23, v22, v169
	v_mov_b32_e32 v97, v155
	v_cvt_pk_fp8_f32 v97, v21, v23
	v_mul_f32_e32 v21, v22, v37
	v_mul_f32_e32 v22, v22, v129
	v_max_f32_e64 v37, s72, s72
	v_cvt_pk_fp8_f32 v97, v21, v22 op_sel:[0,0,1]
	v_mov_b32_e32 v21, s1
	v_cndmask_b32_e32 v23, 0, v21, vcc
	v_cndmask_b32_e32 v22, 0, v20, vcc
	v_cmp_ne_u32_e32 vcc, -1, v35
	s_nop 1
	v_cndmask_b32_e32 v20, 0, v35, vcc
	v_max_f32_e64 v35, s94, s94
	v_max_f32_e32 v35, v37, v35
	v_max_f32_e64 v37, s73, s73
	v_max_f32_e32 v37, v55, v37
	v_max3_f32 v35, v35, v37, s12
	v_div_scale_f32 v37, s[0:1], v35, v35, s13
	v_rcp_f32_e32 v55, v37
	v_cndmask_b32_e32 v21, 0, v21, vcc
	v_fma_f32 v129, -v37, v55, 1.0
	v_fmac_f32_e32 v55, v129, v55
	v_div_scale_f32 v129, vcc, s13, v35, s13
	v_mul_f32_e32 v169, v129, v55
	v_fma_f32 v170, -v37, v169, v129
	v_fmac_f32_e32 v169, v170, v55
	v_fma_f32 v37, -v37, v169, v129
	v_div_fmas_f32 v37, v37, v55, v169
	v_div_fixup_f32 v37, v37, v35, s13
	v_mul_f32_e32 v129, 0x3b888889, v35
	v_mul_f32_e32 v35, v37, v98
	v_mul_f32_e32 v55, v37, v168
	v_mov_b32_e32 v98, v155
	v_cvt_pk_fp8_f32 v98, v35, v55
	v_mul_f32_e32 v35, v37, v99
	v_mul_f32_e32 v55, v37, v163
	v_mov_b32_e32 v99, v155
	v_cvt_pk_fp8_f32 v98, v35, v55 op_sel:[0,0,1]
	v_mul_f32_e32 v35, v37, v164
	v_mul_f32_e32 v55, v37, v165
	v_cvt_pk_fp8_f32 v99, v35, v55
	v_mul_f32_e32 v35, v37, v166
	v_mul_f32_e32 v55, v37, v167
	v_cvt_pk_fp8_f32 v99, v35, v55 op_sel:[0,0,1]
	v_mul_f32_e32 v35, v37, v100
	v_mul_f32_e32 v55, v37, v162
	v_mov_b32_e32 v100, v155
	v_cvt_pk_fp8_f32 v100, v35, v55
	v_mul_f32_e32 v35, v37, v101
	v_mul_f32_e32 v55, v37, v136
	v_mov_b32_e32 v101, v155
	v_cvt_pk_fp8_f32 v100, v35, v55 op_sel:[0,0,1]
	v_mul_f32_e32 v35, v37, v153
	v_mul_f32_e32 v55, v37, v154
	v_cvt_pk_fp8_f32 v101, v35, v55
	v_mul_f32_e32 v35, v37, v160
	v_mul_f32_e32 v37, v37, v161
	v_max_f32_e64 v55, s17, s17
	v_cvt_pk_fp8_f32 v101, v35, v37 op_sel:[0,0,1]
	v_max_f32_e64 v35, s19, s19
	v_max_f32_e64 v37, s75, s75
	v_max_f32_e32 v35, v37, v35
	v_max_f32_e64 v37, s18, s18
	v_max_f32_e32 v37, v55, v37
	v_max3_f32 v35, v35, v37, s12
	v_div_scale_f32 v37, s[0:1], v35, v35, s13
	v_rcp_f32_e32 v55, v37
	s_nop 0
	v_fma_f32 v136, -v37, v55, 1.0
	v_fmac_f32_e32 v55, v136, v55
	v_div_scale_f32 v136, vcc, s13, v35, s13
	v_mul_f32_e32 v153, v136, v55
	v_fma_f32 v154, -v37, v153, v136
	v_fmac_f32_e32 v153, v154, v55
	v_fma_f32 v37, -v37, v153, v136
	v_div_fmas_f32 v37, v37, v55, v153
	v_div_fixup_f32 v37, v37, v35, s13
	v_mul_f32_e32 v136, 0x3b888889, v35
	v_mul_f32_e32 v35, v37, v102
	v_mul_f32_e32 v55, v37, v152
	v_mov_b32_e32 v102, v155
	v_cvt_pk_fp8_f32 v102, v35, v55
	v_mul_f32_e32 v35, v37, v103
	v_mul_f32_e32 v55, v37, v147
	v_mov_b32_e32 v103, v155
	v_cvt_pk_fp8_f32 v102, v35, v55 op_sel:[0,0,1]
	v_mul_f32_e32 v35, v37, v148
	v_mul_f32_e32 v55, v37, v149
	v_cvt_pk_fp8_f32 v103, v35, v55
	v_mul_f32_e32 v35, v37, v150
	v_mul_f32_e32 v55, v37, v151
	v_cvt_pk_fp8_f32 v103, v35, v55 op_sel:[0,0,1]
	v_mul_f32_e32 v35, v37, v104
	v_mul_f32_e32 v55, v37, v146
	v_mov_b32_e32 v104, v155
	v_cvt_pk_fp8_f32 v104, v35, v55
	v_mul_f32_e32 v35, v37, v105
	v_mul_f32_e32 v55, v37, v137
	v_mov_b32_e32 v105, v155
	v_cvt_pk_fp8_f32 v104, v35, v55 op_sel:[0,0,1]
	v_mul_f32_e32 v35, v37, v142
	v_mul_f32_e32 v55, v37, v143
	v_cvt_pk_fp8_f32 v105, v35, v55
	v_mul_f32_e32 v35, v37, v144
	v_mul_f32_e32 v37, v37, v145
	v_max_f32_e64 v55, s31, s31
	v_cvt_pk_fp8_f32 v105, v35, v37 op_sel:[0,0,1]
	v_max_f32_e64 v35, s16, s16
	v_max_f32_e64 v37, s10, s10
	v_max_f32_e32 v35, v37, v35
	v_max_f32_e64 v37, s11, s11
	v_max_f32_e32 v37, v55, v37
	v_max3_f32 v35, v35, v37, s12
	v_div_scale_f32 v37, s[0:1], v35, v35, s13
	v_rcp_f32_e32 v55, v37
	s_bfe_i32 s10, s96, 0x10000
	v_fma_f32 v137, -v37, v55, 1.0
	v_fmac_f32_e32 v55, v137, v55
	v_div_scale_f32 v137, vcc, s13, v35, s13
	v_mul_f32_e32 v142, v137, v55
	v_fma_f32 v143, -v37, v142, v137
	v_fmac_f32_e32 v142, v143, v55
	v_fma_f32 v37, -v37, v142, v137
	v_div_fmas_f32 v37, v37, v55, v142
	v_div_fixup_f32 v37, v37, v35, s13
	v_mul_f32_e32 v137, 0x3b888889, v35
	v_mul_f32_e32 v35, v37, v106
	v_mul_f32_e32 v55, v37, v141
	v_mov_b32_e32 v106, v155
	v_cvt_pk_fp8_f32 v106, v35, v55
	v_mul_f32_e32 v35, v37, v107
	v_mul_f32_e32 v55, v37, v126
	v_mov_b32_e32 v107, v155
	v_cvt_pk_fp8_f32 v106, v35, v55 op_sel:[0,0,1]
	v_mul_f32_e32 v35, v37, v127
	v_mul_f32_e32 v55, v37, v138
	v_cvt_pk_fp8_f32 v107, v35, v55
	v_mul_f32_e32 v35, v37, v139
	v_mul_f32_e32 v55, v37, v140
	v_cvt_pk_fp8_f32 v107, v35, v55 op_sel:[0,0,1]
	v_mul_f32_e32 v35, v37, v108
	v_mul_f32_e32 v55, v37, v125
	v_mov_b32_e32 v108, v155
	v_cvt_pk_fp8_f32 v108, v35, v55
	v_mul_f32_e32 v35, v37, v109
	v_mul_f32_e32 v55, v37, v120
	v_mov_b32_e32 v109, v155
	v_cvt_pk_fp8_f32 v108, v35, v55 op_sel:[0,0,1]
	v_mul_f32_e32 v35, v37, v121
	v_mul_f32_e32 v55, v37, v122
	v_cvt_pk_fp8_f32 v109, v35, v55
	v_mul_f32_e32 v35, v37, v123
	v_mul_f32_e32 v37, v37, v124
	v_max_f32_e64 v55, s97, s97
	v_cvt_pk_fp8_f32 v109, v35, v37 op_sel:[0,0,1]
	v_max_f32_e64 v35, s30, s30
	v_max_f32_e64 v37, s20, s20
	v_max_f32_e32 v35, v37, v35
	v_max_f32_e64 v37, s21, s21
	v_max_f32_e32 v37, v55, v37
	v_max3_f32 v35, v35, v37, s12
	v_div_scale_f32 v37, s[0:1], v35, v35, s13
	v_rcp_f32_e32 v55, v37
	v_mul_f32_e32 v138, 0x3b888889, v35
	v_mov_b32_e32 v123, v155
	v_mov_b32_e32 v124, v155
	v_fma_f32 v120, -v37, v55, 1.0
	v_fmac_f32_e32 v55, v120, v55
	v_div_scale_f32 v120, vcc, s13, v35, s13
	v_mul_f32_e32 v121, v120, v55
	v_fma_f32 v122, -v37, v121, v120
	v_fmac_f32_e32 v121, v122, v55
	v_fma_f32 v37, -v37, v121, v120
	v_div_fmas_f32 v37, v37, v55, v121
	v_div_fixup_f32 v37, v37, v35, s13
	v_mul_f32_e32 v35, v37, v110
	v_mul_f32_e32 v55, v37, v119
	v_mov_b32_e32 v110, v155
	v_cvt_pk_fp8_f32 v110, v35, v55
	v_mul_f32_e32 v35, v37, v111
	v_mul_f32_e32 v55, v37, v114
	v_mov_b32_e32 v111, v155
	v_cvt_pk_fp8_f32 v110, v35, v55 op_sel:[0,0,1]
	v_mul_f32_e32 v35, v37, v115
	v_mul_f32_e32 v55, v37, v116
	v_cvt_pk_fp8_f32 v111, v35, v55
	v_mul_f32_e32 v35, v37, v117
	v_mul_f32_e32 v55, v37, v118
	v_mov_b32_e32 v114, v155
	v_cvt_pk_fp8_f32 v111, v35, v55 op_sel:[0,0,1]
	v_mul_f32_e32 v35, v37, v112
	v_mul_f32_e32 v55, v37, v113
	v_mov_b32_e32 v112, v155
	v_cvt_pk_fp8_f32 v112, v35, v55
	v_mul_f32_e32 v35, v37, v88
	v_mul_f32_e32 v55, v37, v89
	v_mov_b32_e32 v113, v155
	v_cvt_pk_fp8_f32 v112, v35, v55 op_sel:[0,0,1]
	v_mul_f32_e32 v35, v37, v90
	v_mul_f32_e32 v55, v37, v91
	v_cvt_pk_fp8_f32 v113, v35, v55
	v_mul_f32_e32 v35, v37, v92
	v_mul_f32_e32 v37, v37, v93
	v_max_f32_e64 v55, s90, s90
	v_cvt_pk_fp8_f32 v113, v35, v37 op_sel:[0,0,1]
	v_max_f32_e64 v35, s92, s92
	v_max_f32_e64 v37, s74, s74
	v_max_f32_e32 v35, v37, v35
	v_max_f32_e64 v37, s91, s91
	v_max_f32_e32 v37, v55, v37
	v_max3_f32 v35, v35, v37, s12
	v_div_scale_f32 v37, s[0:1], v35, v35, s13
	v_rcp_f32_e32 v55, v37
	v_mul_f32_e32 v139, 0x3b888889, v35
	v_mov_b32_e32 v115, v155
	v_mov_b32_e32 v116, v155
	v_fma_f32 v88, -v37, v55, 1.0
	v_fmac_f32_e32 v55, v88, v55
	v_div_scale_f32 v88, vcc, s13, v35, s13
	v_mul_f32_e32 v89, v88, v55
	v_fma_f32 v90, -v37, v89, v88
	v_fmac_f32_e32 v89, v90, v55
	v_fma_f32 v37, -v37, v89, v88
	v_div_fmas_f32 v37, v37, v55, v89
	v_div_fixup_f32 v37, v37, v35, s13
	v_mul_f32_e32 v35, v37, v80
	v_mul_f32_e32 v55, v37, v81
	v_cvt_pk_fp8_f32 v114, v35, v55
	v_mul_f32_e32 v35, v37, v82
	v_mul_f32_e32 v55, v37, v83
	v_mov_b32_e32 v117, v155
	v_cvt_pk_fp8_f32 v114, v35, v55 op_sel:[0,0,1]
	v_mul_f32_e32 v35, v37, v84
	v_mul_f32_e32 v55, v37, v85
	v_cvt_pk_fp8_f32 v115, v35, v55
	v_mul_f32_e32 v35, v37, v86
	v_mul_f32_e32 v55, v37, v87
	v_readlane_b32 s0, v254, 44
	v_cvt_pk_fp8_f32 v115, v35, v55 op_sel:[0,0,1]
	v_mul_f32_e32 v35, v37, v72
	v_mul_f32_e32 v55, v37, v73
	v_cvt_pk_fp8_f32 v116, v35, v55
	v_mul_f32_e32 v35, v37, v74
	v_mul_f32_e32 v55, v37, v75
	v_mov_b32_e32 v118, v155
	v_cvt_pk_fp8_f32 v116, v35, v55 op_sel:[0,0,1]
	v_mul_f32_e32 v35, v37, v76
	v_mul_f32_e32 v55, v37, v77
	v_cvt_pk_fp8_f32 v117, v35, v55
	v_mul_f32_e32 v35, v37, v78
	v_mul_f32_e32 v37, v37, v79
	v_max_f32_e64 v55, s0, s0
	v_cvt_pk_fp8_f32 v117, v35, v37 op_sel:[0,0,1]
	v_max_f32_e64 v35, s37, s37
	v_max_f32_e64 v37, s35, s35
	v_max_f32_e32 v35, v37, v35
	v_max_f32_e64 v37, s36, s36
	v_max_f32_e32 v37, v55, v37
	v_max3_f32 v35, v35, v37, s12
	v_div_scale_f32 v37, s[0:1], v35, v35, s13
	v_rcp_f32_e32 v55, v37
	v_mul_f32_e32 v140, 0x3b888889, v35
	v_mov_b32_e32 v119, v155
	v_mov_b32_e32 v120, v155
	v_fma_f32 v72, -v37, v55, 1.0
	v_fmac_f32_e32 v55, v72, v55
	v_div_scale_f32 v72, vcc, s13, v35, s13
	v_mul_f32_e32 v73, v72, v55
	v_fma_f32 v74, -v37, v73, v72
	v_fmac_f32_e32 v73, v74, v55
	v_fma_f32 v37, -v37, v73, v72
	v_div_fmas_f32 v37, v37, v55, v73
	v_div_fixup_f32 v37, v37, v35, s13
	v_mul_f32_e32 v35, v37, v64
	v_mul_f32_e32 v55, v37, v65
	v_cvt_pk_fp8_f32 v118, v35, v55
	v_mul_f32_e32 v35, v37, v66
	v_mul_f32_e32 v55, v37, v67
	v_mov_b32_e32 v121, v155
	v_cvt_pk_fp8_f32 v118, v35, v55 op_sel:[0,0,1]
	v_mul_f32_e32 v35, v37, v68
	v_mul_f32_e32 v55, v37, v69
	v_cvt_pk_fp8_f32 v119, v35, v55
	v_mul_f32_e32 v35, v37, v70
	v_mul_f32_e32 v55, v37, v71
	v_readlane_b32 s0, v254, 42
	v_cvt_pk_fp8_f32 v119, v35, v55 op_sel:[0,0,1]
	v_mul_f32_e32 v35, v37, v56
	v_mul_f32_e32 v55, v37, v57
	v_cvt_pk_fp8_f32 v120, v35, v55
	v_mul_f32_e32 v35, v37, v58
	v_mul_f32_e32 v55, v37, v59
	v_mov_b32_e32 v122, v155
	v_cvt_pk_fp8_f32 v120, v35, v55 op_sel:[0,0,1]
	v_mul_f32_e32 v35, v37, v60
	v_mul_f32_e32 v55, v37, v61
	v_cvt_pk_fp8_f32 v121, v35, v55
	v_mul_f32_e32 v35, v37, v62
	v_mul_f32_e32 v37, v37, v63
	v_mov_b32_e32 v125, v155
	v_cvt_pk_fp8_f32 v121, v35, v37 op_sel:[0,0,1]
	v_max_f32_e64 v35, s0, s0
	v_readlane_b32 s0, v254, 38
	s_mov_b32 s36, 30
	s_nop 0
	v_max_f32_e64 v37, s0, s0
	v_readlane_b32 s0, v254, 40
	v_max_f32_e32 v35, v37, v35
	s_nop 0
	v_max_f32_e64 v37, s0, s0
	v_readlane_b32 s0, v254, 36
	s_nop 1
	v_max_f32_e64 v55, s0, s0
	v_max_f32_e32 v37, v55, v37
	v_max3_f32 v35, v35, v37, s12
	v_div_scale_f32 v37, s[0:1], v35, v35, s13
	v_rcp_f32_e32 v55, v37
	v_mul_f32_e32 v141, 0x3b888889, v35
	s_and_b32 s0, s96, 1
	s_cmp_eq_u32 s0, 0
	v_fma_f32 v56, -v37, v55, 1.0
	v_fmac_f32_e32 v55, v56, v55
	v_div_scale_f32 v56, vcc, s13, v35, s13
	v_mul_f32_e32 v57, v56, v55
	v_fma_f32 v58, -v37, v57, v56
	v_fmac_f32_e32 v57, v58, v55
	v_fma_f32 v37, -v37, v57, v56
	v_div_fmas_f32 v37, v37, v55, v57
	v_div_fixup_f32 v37, v37, v35, s13
	v_mul_f32_e32 v35, v37, v47
	v_mul_f32_e32 v47, v37, v48
	v_cvt_pk_fp8_f32 v122, v35, v47
	v_mul_f32_e32 v35, v37, v49
	v_mul_f32_e32 v47, v37, v50
	v_mul_f32_e32 v1, v37, v1
	v_cvt_pk_fp8_f32 v122, v35, v47 op_sel:[0,0,1]
	v_mul_f32_e32 v35, v37, v51
	v_mul_f32_e32 v47, v37, v52
	v_cvt_pk_fp8_f32 v123, v35, v47
	v_mul_f32_e32 v35, v37, v53
	v_mul_f32_e32 v47, v37, v54
	s_cselect_b64 s[0:1], -1, 0
	v_cvt_pk_fp8_f32 v123, v35, v47 op_sel:[0,0,1]
	v_mul_f32_e32 v35, v37, v40
	v_cvt_pk_fp8_f32 v124, v1, v35
	v_mul_f32_e32 v1, v37, v41
	v_mul_f32_e32 v35, v37, v42
	s_and_b32 s34, s10, 31
	v_cvt_pk_fp8_f32 v124, v1, v35 op_sel:[0,0,1]
	v_mul_f32_e32 v1, v37, v43
	v_mul_f32_e32 v35, v37, v44
	v_cvt_pk_fp8_f32 v125, v1, v35
	v_mul_f32_e32 v1, v37, v45
	v_mul_f32_e32 v35, v37, v46
	v_ashrrev_i32_e32 v37, 31, v36
	v_cvt_pk_fp8_f32 v125, v1, v35 op_sel:[0,0,1]
	v_add_f32_e32 v1, v33, v34
	v_cvt_u32_f32_e32 v1, v1
	s_lshl_b32 s35, s34, 4
	s_add_i32 s10, s93, s35
	v_mov_b32_e32 v62, s10
	v_sub_u32_e32 v1, v1, v32
	flat_store_dword v[2:3], v1 sc0 sc1
	s_waitcnt vmcnt(0)
	v_add_u32_e32 v1, v1, v26
	flat_store_dword v[4:5], v1 sc0 sc1
	s_waitcnt vmcnt(0)
	v_add_u32_e32 v1, v1, v25
	flat_store_dword v[6:7], v1 sc0 sc1
	s_waitcnt vmcnt(0)
	v_add_u32_e32 v1, v1, v28
	flat_store_dword v[8:9], v1 sc0 sc1
	s_waitcnt vmcnt(0)
	v_add_u32_e32 v1, v1, v27
	flat_store_dword v[10:11], v1 sc0 sc1
	s_waitcnt vmcnt(0)
	v_add_u32_e32 v1, v1, v30
	flat_store_dword v[12:13], v1 sc0 sc1
	s_waitcnt vmcnt(0)
	v_add_u32_e32 v1, v1, v29
	flat_store_dword v[14:15], v1 sc0 sc1
	s_waitcnt vmcnt(0)
	v_add_u32_e32 v1, v1, v31
	flat_store_dword v[16:17], v1 sc0 sc1
	s_waitcnt vmcnt(0)
	s_waitcnt lgkmcnt(0)
	flat_load_dword v1, v[22:23] sc0 sc1
	s_waitcnt vmcnt(0)
	flat_load_dword v2, v[20:21] sc0 sc1
	s_waitcnt vmcnt(0)
	s_waitcnt lgkmcnt(0)
	v_lshl_add_u64 v[4:5], v[36:37], 3, s[28:29]
	global_load_dwordx2 v[4:5], v[4:5], off
	s_waitcnt lgkmcnt(0)
	v_add_u32_e32 v1, v1, v19
	v_ashrrev_i32_e32 v19, 31, v18
	v_add_u32_e32 v6, v2, v24
	v_lshl_add_u64 v[2:3], v[18:19], 3, s[28:29]
	global_load_dwordx2 v[2:3], v[2:3], off
	v_lshl_add_u32 v1, v1, 2, s93
	s_waitcnt vmcnt(0)
	v_mul_f32_e32 v3, v38, v3
	ds_write2st64_b32 v1, v18, v3 offset0:42 offset1:44
	ds_write_b32 v1, v2 offset:11776
	v_lshl_add_u32 v1, v6, 2, s93
	v_mul_f32_e32 v2, v39, v5
	ds_write2st64_b32 v1, v36, v2 offset0:42 offset1:44
	ds_write_b32 v1, v4 offset:11776
	s_waitcnt lgkmcnt(0)
	v_readfirstlane_b32 s98, v130
	v_readfirstlane_b32 s99, v131
	v_lshlrev_b32_e32 v92, 4, v176
	s_mov_b32 s95, 0
	s_cmp_lg_u64 s[0:1], 0
	s_cselect_b32 s34, 0, 31
	s_lshl_b32 s36, s34, 4
	v_add_u32_e32 v89, s36, v181
	s_add_i32 s10, s93, s36
	v_mov_b32_e32 v91, s10
	ds_read_b128 v[66:69], v91 offset:0
	ds_read_b128 v[70:73], v91 offset:1536
	ds_read_b128 v[74:77], v91 offset:3072
	ds_read_b128 v[78:81], v91 offset:4608
	s_waitcnt lgkmcnt(3)
	v_lshl_add_u32 v145, v66, 10, v92
	global_load_dwordx4 v[2:5], v145, s[98:99]
	v_lshl_add_u32 v1, v67, 10, v92
	global_load_dwordx4 v[6:9], v1, s[98:99]
	v_lshl_add_u32 v145, v68, 10, v92
	global_load_dwordx4 v[10:13], v145, s[98:99]
	v_lshl_add_u32 v1, v69, 10, v92
	global_load_dwordx4 v[14:17], v1, s[98:99]
	ds_read_b32 v82, v89 offset:1024
	s_waitcnt lgkmcnt(3)
	v_lshl_add_u32 v145, v70, 10, v92
	global_load_dwordx4 v[18:21], v145, s[98:99]
	v_lshl_add_u32 v1, v71, 10, v92
	global_load_dwordx4 v[22:25], v1, s[98:99]
	v_lshl_add_u32 v145, v72, 10, v92
	global_load_dwordx4 v[26:29], v145, s[98:99]
	v_lshl_add_u32 v1, v73, 10, v92
	global_load_dwordx4 v[30:33], v1, s[98:99]
	ds_read_b32 v83, v89 offset:2560
	s_waitcnt lgkmcnt(3)
	v_lshl_add_u32 v145, v74, 10, v92
	global_load_dwordx4 v[34:37], v145, s[98:99]
	v_lshl_add_u32 v1, v75, 10, v92
	global_load_dwordx4 v[38:41], v1, s[98:99]
	v_lshl_add_u32 v145, v76, 10, v92
	global_load_dwordx4 v[42:45], v145, s[98:99]
	v_lshl_add_u32 v1, v77, 10, v92
	global_load_dwordx4 v[46:49], v1, s[98:99]
	ds_read_b32 v84, v89 offset:4096
	s_waitcnt lgkmcnt(3)
	v_lshl_add_u32 v145, v78, 10, v92
	global_load_dwordx4 v[50:53], v145, s[98:99]
	v_lshl_add_u32 v1, v79, 10, v92
	global_load_dwordx4 v[54:57], v1, s[98:99]
	v_lshl_add_u32 v145, v80, 10, v92
	global_load_dwordx4 v[58:61], v145, s[98:99]
	v_lshl_add_u32 v1, v81, 10, v92
	global_load_dwordx4 v[62:65], v1, s[98:99]
	ds_read_b32 v85, v89 offset:5632
	ds_read_b128 v[66:69], v91 offset:6144
	ds_read_b128 v[70:73], v91 offset:7680
	ds_read_b128 v[74:77], v91 offset:9216
	ds_read_b128 v[78:81], v91 offset:10752
	s_waitcnt lgkmcnt(0)
.Lus_loop:
	s_add_i32 s10, s34, 1
	s_min_u32 s10, s10, 31
	s_sub_i32 s11, s34, 1
	s_max_i32 s11, s11, 0
	s_cmp_lg_u64 s[0:1], 0
	s_cselect_b32 s35, s10, s11
	s_lshl_b32 s36, s35, 4
	v_add_u32_e32 v90, s36, v181
	s_add_i32 s10, s93, s36
	v_mov_b32_e32 v91, s10
	s_barrier
	s_waitcnt vmcnt(12) lgkmcnt(10)
	v_mul_f32_e32 v88, v141, v82
	v_mfma_f32_16x16x32_fp8_fp8 v[184:187], v[2:3], v[122:123], 0
	v_mfma_f32_16x16x32_fp8_fp8 v[188:191], v[6:7], v[122:123], 0
	v_mfma_f32_16x16x32_fp8_fp8 v[192:195], v[10:11], v[122:123], 0
	v_mfma_f32_16x16x32_fp8_fp8 v[196:199], v[14:15], v[122:123], 0
	v_mfma_f32_16x16x32_fp8_fp8 v[184:187], v[4:5], v[124:125], v[184:187]
	v_mfma_f32_16x16x32_fp8_fp8 v[188:191], v[8:9], v[124:125], v[188:191]
	v_mfma_f32_16x16x32_fp8_fp8 v[192:195], v[12:13], v[124:125], v[192:195]
	v_mfma_f32_16x16x32_fp8_fp8 v[196:199], v[16:17], v[124:125], v[196:199]
	v_lshl_add_u32 v145, v66, 10, v92
	global_load_dwordx4 v[2:5], v145, s[98:99]
	v_lshl_add_u32 v1, v67, 10, v92
	global_load_dwordx4 v[6:9], v1, s[98:99]
	v_lshl_add_u32 v145, v68, 10, v92
	global_load_dwordx4 v[10:13], v145, s[98:99]
	v_lshl_add_u32 v1, v69, 10, v92
	global_load_dwordx4 v[14:17], v1, s[98:99]
	ds_read_b32 v82, v89 offset:7168
	ds_read_b128 v[66:69], v91 offset:0
	v_cndmask_b32_e64 v184, v185, v184, s[2:3]
	v_cndmask_b32_e64 v185, v187, v186, s[2:3]
	v_cndmask_b32_e64 v188, v189, v188, s[2:3]
	v_cndmask_b32_e64 v189, v191, v190, s[2:3]
	v_cndmask_b32_e64 v192, v193, v192, s[2:3]
	v_cndmask_b32_e64 v193, v195, v194, s[2:3]
	v_cndmask_b32_e64 v196, v197, v196, s[2:3]
	v_cndmask_b32_e64 v197, v199, v198, s[2:3]
	v_cndmask_b32_e64 v184, v185, v184, s[4:5]
	v_cndmask_b32_e64 v188, v189, v188, s[4:5]
	v_cndmask_b32_e64 v192, v193, v192, s[4:5]
	v_cndmask_b32_e64 v196, v197, v196, s[4:5]
	v_cndmask_b32_e64 v146, v188, v184, s[2:3]
	v_cndmask_b32_e64 v143, v184, v188, s[2:3]
	v_cndmask_b32_e64 v142, v196, v192, s[2:3]
	v_cndmask_b32_e64 v144, v192, v196, s[2:3]
	s_nop 0
	v_add_f32_dpp v146, v143, v146 quad_perm:[1,0,3,2] row_mask:0xf bank_mask:0xf bound_ctrl:1
	v_add_f32_dpp v142, v144, v142 quad_perm:[1,0,3,2] row_mask:0xf bank_mask:0xf bound_ctrl:1
	v_cndmask_b32_e64 v143, v142, v146, s[4:5]
	v_cndmask_b32_e64 v86, v146, v142, s[4:5]
	s_nop 1
	v_add_f32_dpp v86, v86, v143 quad_perm:[2,3,0,1] row_mask:0xf bank_mask:0xf bound_ctrl:1
	v_cndmask_b32_e64 v86, 0, v86, s[6:7]
	s_nop 1
	v_add_f32_dpp v86, v86, v86 row_ror:4 row_mask:0xf bank_mask:0xf bound_ctrl:1
	s_nop 1
	v_add_f32_dpp v86, v86, v86 row_ror:8 row_mask:0xf bank_mask:0xf bound_ctrl:1
	v_mov_b32_e32 v87, v86
	s_nop 1
	v_permlane16_swap_b32_e32 v86, v87
	v_add_f32_e32 v86, v86, v87
	v_mov_b32_e32 v87, v86
	s_nop 1
	v_permlane32_swap_b32 v86, v87
	v_add_f32_e32 v86, v86, v87
	v_mul_f32_e32 v93, v88, v86
	s_mov_b64 exec, s[8:9]
	ds_write_b32 v89, v93 offset:1024
	s_mov_b64 exec, -1
	s_waitcnt vmcnt(12) lgkmcnt(10)
	v_mul_f32_e32 v88, v140, v83
	v_mfma_f32_16x16x32_fp8_fp8 v[184:187], v[18:19], v[118:119], 0
	v_mfma_f32_16x16x32_fp8_fp8 v[188:191], v[22:23], v[118:119], 0
	v_mfma_f32_16x16x32_fp8_fp8 v[192:195], v[26:27], v[118:119], 0
	v_mfma_f32_16x16x32_fp8_fp8 v[196:199], v[30:31], v[118:119], 0
	v_mfma_f32_16x16x32_fp8_fp8 v[184:187], v[20:21], v[120:121], v[184:187]
	v_mfma_f32_16x16x32_fp8_fp8 v[188:191], v[24:25], v[120:121], v[188:191]
	v_mfma_f32_16x16x32_fp8_fp8 v[192:195], v[28:29], v[120:121], v[192:195]
	v_mfma_f32_16x16x32_fp8_fp8 v[196:199], v[32:33], v[120:121], v[196:199]
	v_lshl_add_u32 v145, v70, 10, v92
	global_load_dwordx4 v[18:21], v145, s[98:99]
	v_lshl_add_u32 v1, v71, 10, v92
	global_load_dwordx4 v[22:25], v1, s[98:99]
	v_lshl_add_u32 v145, v72, 10, v92
	global_load_dwordx4 v[26:29], v145, s[98:99]
	v_lshl_add_u32 v1, v73, 10, v92
	global_load_dwordx4 v[30:33], v1, s[98:99]
	ds_read_b32 v83, v89 offset:8704
	ds_read_b128 v[70:73], v91 offset:1536
	v_cndmask_b32_e64 v184, v185, v184, s[2:3]
	v_cndmask_b32_e64 v185, v187, v186, s[2:3]
	v_cndmask_b32_e64 v188, v189, v188, s[2:3]
	v_cndmask_b32_e64 v189, v191, v190, s[2:3]
	v_cndmask_b32_e64 v192, v193, v192, s[2:3]
	v_cndmask_b32_e64 v193, v195, v194, s[2:3]
	v_cndmask_b32_e64 v196, v197, v196, s[2:3]
	v_cndmask_b32_e64 v197, v199, v198, s[2:3]
	v_cndmask_b32_e64 v184, v185, v184, s[4:5]
	v_cndmask_b32_e64 v188, v189, v188, s[4:5]
	v_cndmask_b32_e64 v192, v193, v192, s[4:5]
	v_cndmask_b32_e64 v196, v197, v196, s[4:5]
	v_cndmask_b32_e64 v146, v188, v184, s[2:3]
	v_cndmask_b32_e64 v143, v184, v188, s[2:3]
	v_cndmask_b32_e64 v142, v196, v192, s[2:3]
	v_cndmask_b32_e64 v144, v192, v196, s[2:3]
	s_nop 0
	v_add_f32_dpp v146, v143, v146 quad_perm:[1,0,3,2] row_mask:0xf bank_mask:0xf bound_ctrl:1
	v_add_f32_dpp v142, v144, v142 quad_perm:[1,0,3,2] row_mask:0xf bank_mask:0xf bound_ctrl:1
	v_cndmask_b32_e64 v143, v142, v146, s[4:5]
	v_cndmask_b32_e64 v86, v146, v142, s[4:5]
	s_nop 1
	v_add_f32_dpp v86, v86, v143 quad_perm:[2,3,0,1] row_mask:0xf bank_mask:0xf bound_ctrl:1
	v_cndmask_b32_e64 v86, 0, v86, s[6:7]
	s_nop 1
	v_add_f32_dpp v86, v86, v86 row_ror:4 row_mask:0xf bank_mask:0xf bound_ctrl:1
	s_nop 1
	v_add_f32_dpp v86, v86, v86 row_ror:8 row_mask:0xf bank_mask:0xf bound_ctrl:1
	v_mov_b32_e32 v87, v86
	s_nop 1
	v_permlane16_swap_b32_e32 v86, v87
	v_add_f32_e32 v86, v86, v87
	v_mov_b32_e32 v87, v86
	s_nop 1
	v_permlane32_swap_b32 v86, v87
	v_add_f32_e32 v86, v86, v87
	v_mul_f32_e32 v93, v88, v86
	s_mov_b64 exec, s[8:9]
	ds_write_b32 v89, v93 offset:2560
	s_mov_b64 exec, -1
	s_waitcnt vmcnt(12) lgkmcnt(10)
	v_mul_f32_e32 v88, v139, v84
	v_mfma_f32_16x16x32_fp8_fp8 v[184:187], v[34:35], v[114:115], 0
	v_mfma_f32_16x16x32_fp8_fp8 v[188:191], v[38:39], v[114:115], 0
	v_mfma_f32_16x16x32_fp8_fp8 v[192:195], v[42:43], v[114:115], 0
	v_mfma_f32_16x16x32_fp8_fp8 v[196:199], v[46:47], v[114:115], 0
	v_mfma_f32_16x16x32_fp8_fp8 v[184:187], v[36:37], v[116:117], v[184:187]
	v_mfma_f32_16x16x32_fp8_fp8 v[188:191], v[40:41], v[116:117], v[188:191]
	v_mfma_f32_16x16x32_fp8_fp8 v[192:195], v[44:45], v[116:117], v[192:195]
	v_mfma_f32_16x16x32_fp8_fp8 v[196:199], v[48:49], v[116:117], v[196:199]
	v_lshl_add_u32 v145, v74, 10, v92
	global_load_dwordx4 v[34:37], v145, s[98:99]
	v_lshl_add_u32 v1, v75, 10, v92
	global_load_dwordx4 v[38:41], v1, s[98:99]
	v_lshl_add_u32 v145, v76, 10, v92
	global_load_dwordx4 v[42:45], v145, s[98:99]
	v_lshl_add_u32 v1, v77, 10, v92
	global_load_dwordx4 v[46:49], v1, s[98:99]
	ds_read_b32 v84, v89 offset:10240
	ds_read_b128 v[74:77], v91 offset:3072
	v_cndmask_b32_e64 v184, v185, v184, s[2:3]
	v_cndmask_b32_e64 v185, v187, v186, s[2:3]
	v_cndmask_b32_e64 v188, v189, v188, s[2:3]
	v_cndmask_b32_e64 v189, v191, v190, s[2:3]
	v_cndmask_b32_e64 v192, v193, v192, s[2:3]
	v_cndmask_b32_e64 v193, v195, v194, s[2:3]
	v_cndmask_b32_e64 v196, v197, v196, s[2:3]
	v_cndmask_b32_e64 v197, v199, v198, s[2:3]
	v_cndmask_b32_e64 v184, v185, v184, s[4:5]
	v_cndmask_b32_e64 v188, v189, v188, s[4:5]
	v_cndmask_b32_e64 v192, v193, v192, s[4:5]
	v_cndmask_b32_e64 v196, v197, v196, s[4:5]
	v_cndmask_b32_e64 v146, v188, v184, s[2:3]
	v_cndmask_b32_e64 v143, v184, v188, s[2:3]
	v_cndmask_b32_e64 v142, v196, v192, s[2:3]
	v_cndmask_b32_e64 v144, v192, v196, s[2:3]
	s_nop 0
	v_add_f32_dpp v146, v143, v146 quad_perm:[1,0,3,2] row_mask:0xf bank_mask:0xf bound_ctrl:1
	v_add_f32_dpp v142, v144, v142 quad_perm:[1,0,3,2] row_mask:0xf bank_mask:0xf bound_ctrl:1
	v_cndmask_b32_e64 v143, v142, v146, s[4:5]
	v_cndmask_b32_e64 v86, v146, v142, s[4:5]
	s_nop 1
	v_add_f32_dpp v86, v86, v143 quad_perm:[2,3,0,1] row_mask:0xf bank_mask:0xf bound_ctrl:1
	v_cndmask_b32_e64 v86, 0, v86, s[6:7]
	s_nop 1
	v_add_f32_dpp v86, v86, v86 row_ror:4 row_mask:0xf bank_mask:0xf bound_ctrl:1
	s_nop 1
	v_add_f32_dpp v86, v86, v86 row_ror:8 row_mask:0xf bank_mask:0xf bound_ctrl:1
	v_mov_b32_e32 v87, v86
	s_nop 1
	v_permlane16_swap_b32_e32 v86, v87
	v_add_f32_e32 v86, v86, v87
	v_mov_b32_e32 v87, v86
	s_nop 1
	v_permlane32_swap_b32 v86, v87
	v_add_f32_e32 v86, v86, v87
	v_mul_f32_e32 v93, v88, v86
	s_mov_b64 exec, s[8:9]
	ds_write_b32 v89, v93 offset:4096
	s_mov_b64 exec, -1
	s_waitcnt vmcnt(12) lgkmcnt(10)
	v_mul_f32_e32 v88, v138, v85
	v_mfma_f32_16x16x32_fp8_fp8 v[184:187], v[50:51], v[110:111], 0
	v_mfma_f32_16x16x32_fp8_fp8 v[188:191], v[54:55], v[110:111], 0
	v_mfma_f32_16x16x32_fp8_fp8 v[192:195], v[58:59], v[110:111], 0
	v_mfma_f32_16x16x32_fp8_fp8 v[196:199], v[62:63], v[110:111], 0
	v_mfma_f32_16x16x32_fp8_fp8 v[184:187], v[52:53], v[112:113], v[184:187]
	v_mfma_f32_16x16x32_fp8_fp8 v[188:191], v[56:57], v[112:113], v[188:191]
	v_mfma_f32_16x16x32_fp8_fp8 v[192:195], v[60:61], v[112:113], v[192:195]
	v_mfma_f32_16x16x32_fp8_fp8 v[196:199], v[64:65], v[112:113], v[196:199]
	v_lshl_add_u32 v145, v78, 10, v92
	global_load_dwordx4 v[50:53], v145, s[98:99]
	v_lshl_add_u32 v1, v79, 10, v92
	global_load_dwordx4 v[54:57], v1, s[98:99]
	v_lshl_add_u32 v145, v80, 10, v92
	global_load_dwordx4 v[58:61], v145, s[98:99]
	v_lshl_add_u32 v1, v81, 10, v92
	global_load_dwordx4 v[62:65], v1, s[98:99]
	ds_read_b32 v85, v89 offset:11776
	ds_read_b128 v[78:81], v91 offset:4608
	v_cndmask_b32_e64 v184, v185, v184, s[2:3]
	v_cndmask_b32_e64 v185, v187, v186, s[2:3]
	v_cndmask_b32_e64 v188, v189, v188, s[2:3]
	v_cndmask_b32_e64 v189, v191, v190, s[2:3]
	v_cndmask_b32_e64 v192, v193, v192, s[2:3]
	v_cndmask_b32_e64 v193, v195, v194, s[2:3]
	v_cndmask_b32_e64 v196, v197, v196, s[2:3]
	v_cndmask_b32_e64 v197, v199, v198, s[2:3]
	v_cndmask_b32_e64 v184, v185, v184, s[4:5]
	v_cndmask_b32_e64 v188, v189, v188, s[4:5]
	v_cndmask_b32_e64 v192, v193, v192, s[4:5]
	v_cndmask_b32_e64 v196, v197, v196, s[4:5]
	v_cndmask_b32_e64 v146, v188, v184, s[2:3]
	v_cndmask_b32_e64 v143, v184, v188, s[2:3]
	v_cndmask_b32_e64 v142, v196, v192, s[2:3]
	v_cndmask_b32_e64 v144, v192, v196, s[2:3]
	s_nop 0
	v_add_f32_dpp v146, v143, v146 quad_perm:[1,0,3,2] row_mask:0xf bank_mask:0xf bound_ctrl:1
	v_add_f32_dpp v142, v144, v142 quad_perm:[1,0,3,2] row_mask:0xf bank_mask:0xf bound_ctrl:1
	v_cndmask_b32_e64 v143, v142, v146, s[4:5]
	v_cndmask_b32_e64 v86, v146, v142, s[4:5]
	s_nop 1
	v_add_f32_dpp v86, v86, v143 quad_perm:[2,3,0,1] row_mask:0xf bank_mask:0xf bound_ctrl:1
	v_cndmask_b32_e64 v86, 0, v86, s[6:7]
	s_nop 1
	v_add_f32_dpp v86, v86, v86 row_ror:4 row_mask:0xf bank_mask:0xf bound_ctrl:1
	s_nop 1
	v_add_f32_dpp v86, v86, v86 row_ror:8 row_mask:0xf bank_mask:0xf bound_ctrl:1
	v_mov_b32_e32 v87, v86
	s_nop 1
	v_permlane16_swap_b32_e32 v86, v87
	v_add_f32_e32 v86, v86, v87
	v_mov_b32_e32 v87, v86
	s_nop 1
	v_permlane32_swap_b32 v86, v87
	v_add_f32_e32 v86, v86, v87
	v_mul_f32_e32 v93, v88, v86
	s_mov_b64 exec, s[8:9]
	ds_write_b32 v89, v93 offset:5632
	s_mov_b64 exec, -1
	s_waitcnt vmcnt(12) lgkmcnt(10)
	v_mul_f32_e32 v88, v137, v82
	v_mfma_f32_16x16x32_fp8_fp8 v[184:187], v[2:3], v[106:107], 0
	v_mfma_f32_16x16x32_fp8_fp8 v[188:191], v[6:7], v[106:107], 0
	v_mfma_f32_16x16x32_fp8_fp8 v[192:195], v[10:11], v[106:107], 0
	v_mfma_f32_16x16x32_fp8_fp8 v[196:199], v[14:15], v[106:107], 0
	v_mfma_f32_16x16x32_fp8_fp8 v[184:187], v[4:5], v[108:109], v[184:187]
	v_mfma_f32_16x16x32_fp8_fp8 v[188:191], v[8:9], v[108:109], v[188:191]
	v_mfma_f32_16x16x32_fp8_fp8 v[192:195], v[12:13], v[108:109], v[192:195]
	v_mfma_f32_16x16x32_fp8_fp8 v[196:199], v[16:17], v[108:109], v[196:199]
	v_lshl_add_u32 v145, v66, 10, v92
	global_load_dwordx4 v[2:5], v145, s[98:99]
	v_lshl_add_u32 v1, v67, 10, v92
	global_load_dwordx4 v[6:9], v1, s[98:99]
	v_lshl_add_u32 v145, v68, 10, v92
	global_load_dwordx4 v[10:13], v145, s[98:99]
	v_lshl_add_u32 v1, v69, 10, v92
	global_load_dwordx4 v[14:17], v1, s[98:99]
	ds_read_b32 v82, v90 offset:1024
	ds_read_b128 v[66:69], v91 offset:6144
	v_cndmask_b32_e64 v184, v185, v184, s[2:3]
	v_cndmask_b32_e64 v185, v187, v186, s[2:3]
	v_cndmask_b32_e64 v188, v189, v188, s[2:3]
	v_cndmask_b32_e64 v189, v191, v190, s[2:3]
	v_cndmask_b32_e64 v192, v193, v192, s[2:3]
	v_cndmask_b32_e64 v193, v195, v194, s[2:3]
	v_cndmask_b32_e64 v196, v197, v196, s[2:3]
	v_cndmask_b32_e64 v197, v199, v198, s[2:3]
	v_cndmask_b32_e64 v184, v185, v184, s[4:5]
	v_cndmask_b32_e64 v188, v189, v188, s[4:5]
	v_cndmask_b32_e64 v192, v193, v192, s[4:5]
	v_cndmask_b32_e64 v196, v197, v196, s[4:5]
	v_cndmask_b32_e64 v146, v188, v184, s[2:3]
	v_cndmask_b32_e64 v143, v184, v188, s[2:3]
	v_cndmask_b32_e64 v142, v196, v192, s[2:3]
	v_cndmask_b32_e64 v144, v192, v196, s[2:3]
	s_nop 0
	v_add_f32_dpp v146, v143, v146 quad_perm:[1,0,3,2] row_mask:0xf bank_mask:0xf bound_ctrl:1
	v_add_f32_dpp v142, v144, v142 quad_perm:[1,0,3,2] row_mask:0xf bank_mask:0xf bound_ctrl:1
	v_cndmask_b32_e64 v143, v142, v146, s[4:5]
	v_cndmask_b32_e64 v86, v146, v142, s[4:5]
	s_nop 1
	v_add_f32_dpp v86, v86, v143 quad_perm:[2,3,0,1] row_mask:0xf bank_mask:0xf bound_ctrl:1
	v_cndmask_b32_e64 v86, 0, v86, s[6:7]
	s_nop 1
	v_add_f32_dpp v86, v86, v86 row_ror:4 row_mask:0xf bank_mask:0xf bound_ctrl:1
	s_nop 1
	v_add_f32_dpp v86, v86, v86 row_ror:8 row_mask:0xf bank_mask:0xf bound_ctrl:1
	v_mov_b32_e32 v87, v86
	s_nop 1
	v_permlane16_swap_b32_e32 v86, v87
	v_add_f32_e32 v86, v86, v87
	v_mov_b32_e32 v87, v86
	s_nop 1
	v_permlane32_swap_b32 v86, v87
	v_add_f32_e32 v86, v86, v87
	v_mul_f32_e32 v93, v88, v86
	s_mov_b64 exec, s[8:9]
	ds_write_b32 v89, v93 offset:7168
	s_mov_b64 exec, -1
	s_waitcnt vmcnt(12) lgkmcnt(10)
	v_mul_f32_e32 v88, v136, v83
	v_mfma_f32_16x16x32_fp8_fp8 v[184:187], v[18:19], v[102:103], 0
	v_mfma_f32_16x16x32_fp8_fp8 v[188:191], v[22:23], v[102:103], 0
	v_mfma_f32_16x16x32_fp8_fp8 v[192:195], v[26:27], v[102:103], 0
	v_mfma_f32_16x16x32_fp8_fp8 v[196:199], v[30:31], v[102:103], 0
	v_mfma_f32_16x16x32_fp8_fp8 v[184:187], v[20:21], v[104:105], v[184:187]
	v_mfma_f32_16x16x32_fp8_fp8 v[188:191], v[24:25], v[104:105], v[188:191]
	v_mfma_f32_16x16x32_fp8_fp8 v[192:195], v[28:29], v[104:105], v[192:195]
	v_mfma_f32_16x16x32_fp8_fp8 v[196:199], v[32:33], v[104:105], v[196:199]
	v_lshl_add_u32 v145, v70, 10, v92
	global_load_dwordx4 v[18:21], v145, s[98:99]
	v_lshl_add_u32 v1, v71, 10, v92
	global_load_dwordx4 v[22:25], v1, s[98:99]
	v_lshl_add_u32 v145, v72, 10, v92
	global_load_dwordx4 v[26:29], v145, s[98:99]
	v_lshl_add_u32 v1, v73, 10, v92
	global_load_dwordx4 v[30:33], v1, s[98:99]
	ds_read_b32 v83, v90 offset:2560
	ds_read_b128 v[70:73], v91 offset:7680
	v_cndmask_b32_e64 v184, v185, v184, s[2:3]
	v_cndmask_b32_e64 v185, v187, v186, s[2:3]
	v_cndmask_b32_e64 v188, v189, v188, s[2:3]
	v_cndmask_b32_e64 v189, v191, v190, s[2:3]
	v_cndmask_b32_e64 v192, v193, v192, s[2:3]
	v_cndmask_b32_e64 v193, v195, v194, s[2:3]
	v_cndmask_b32_e64 v196, v197, v196, s[2:3]
	v_cndmask_b32_e64 v197, v199, v198, s[2:3]
	v_cndmask_b32_e64 v184, v185, v184, s[4:5]
	v_cndmask_b32_e64 v188, v189, v188, s[4:5]
	v_cndmask_b32_e64 v192, v193, v192, s[4:5]
	v_cndmask_b32_e64 v196, v197, v196, s[4:5]
	v_cndmask_b32_e64 v146, v188, v184, s[2:3]
	v_cndmask_b32_e64 v143, v184, v188, s[2:3]
	v_cndmask_b32_e64 v142, v196, v192, s[2:3]
	v_cndmask_b32_e64 v144, v192, v196, s[2:3]
	s_nop 0
	v_add_f32_dpp v146, v143, v146 quad_perm:[1,0,3,2] row_mask:0xf bank_mask:0xf bound_ctrl:1
	v_add_f32_dpp v142, v144, v142 quad_perm:[1,0,3,2] row_mask:0xf bank_mask:0xf bound_ctrl:1
	v_cndmask_b32_e64 v143, v142, v146, s[4:5]
	v_cndmask_b32_e64 v86, v146, v142, s[4:5]
	s_nop 1
	v_add_f32_dpp v86, v86, v143 quad_perm:[2,3,0,1] row_mask:0xf bank_mask:0xf bound_ctrl:1
	v_cndmask_b32_e64 v86, 0, v86, s[6:7]
	s_nop 1
	v_add_f32_dpp v86, v86, v86 row_ror:4 row_mask:0xf bank_mask:0xf bound_ctrl:1
	s_nop 1
	v_add_f32_dpp v86, v86, v86 row_ror:8 row_mask:0xf bank_mask:0xf bound_ctrl:1
	v_mov_b32_e32 v87, v86
	s_nop 1
	v_permlane16_swap_b32_e32 v86, v87
	v_add_f32_e32 v86, v86, v87
	v_mov_b32_e32 v87, v86
	s_nop 1
	v_permlane32_swap_b32 v86, v87
	v_add_f32_e32 v86, v86, v87
	v_mul_f32_e32 v93, v88, v86
	s_mov_b64 exec, s[8:9]
	ds_write_b32 v89, v93 offset:8704
	s_mov_b64 exec, -1
	s_waitcnt vmcnt(12) lgkmcnt(10)
	v_mul_f32_e32 v88, v129, v84
	v_mfma_f32_16x16x32_fp8_fp8 v[184:187], v[34:35], v[98:99], 0
	v_mfma_f32_16x16x32_fp8_fp8 v[188:191], v[38:39], v[98:99], 0
	v_mfma_f32_16x16x32_fp8_fp8 v[192:195], v[42:43], v[98:99], 0
	v_mfma_f32_16x16x32_fp8_fp8 v[196:199], v[46:47], v[98:99], 0
	v_mfma_f32_16x16x32_fp8_fp8 v[184:187], v[36:37], v[100:101], v[184:187]
	v_mfma_f32_16x16x32_fp8_fp8 v[188:191], v[40:41], v[100:101], v[188:191]
	v_mfma_f32_16x16x32_fp8_fp8 v[192:195], v[44:45], v[100:101], v[192:195]
	v_mfma_f32_16x16x32_fp8_fp8 v[196:199], v[48:49], v[100:101], v[196:199]
	v_lshl_add_u32 v145, v74, 10, v92
	global_load_dwordx4 v[34:37], v145, s[98:99]
	v_lshl_add_u32 v1, v75, 10, v92
	global_load_dwordx4 v[38:41], v1, s[98:99]
	v_lshl_add_u32 v145, v76, 10, v92
	global_load_dwordx4 v[42:45], v145, s[98:99]
	v_lshl_add_u32 v1, v77, 10, v92
	global_load_dwordx4 v[46:49], v1, s[98:99]
	ds_read_b32 v84, v90 offset:4096
	ds_read_b128 v[74:77], v91 offset:9216
	v_cndmask_b32_e64 v184, v185, v184, s[2:3]
	v_cndmask_b32_e64 v185, v187, v186, s[2:3]
	v_cndmask_b32_e64 v188, v189, v188, s[2:3]
	v_cndmask_b32_e64 v189, v191, v190, s[2:3]
	v_cndmask_b32_e64 v192, v193, v192, s[2:3]
	v_cndmask_b32_e64 v193, v195, v194, s[2:3]
	v_cndmask_b32_e64 v196, v197, v196, s[2:3]
	v_cndmask_b32_e64 v197, v199, v198, s[2:3]
	v_cndmask_b32_e64 v184, v185, v184, s[4:5]
	v_cndmask_b32_e64 v188, v189, v188, s[4:5]
	v_cndmask_b32_e64 v192, v193, v192, s[4:5]
	v_cndmask_b32_e64 v196, v197, v196, s[4:5]
	v_cndmask_b32_e64 v146, v188, v184, s[2:3]
	v_cndmask_b32_e64 v143, v184, v188, s[2:3]
	v_cndmask_b32_e64 v142, v196, v192, s[2:3]
	v_cndmask_b32_e64 v144, v192, v196, s[2:3]
	s_nop 0
	v_add_f32_dpp v146, v143, v146 quad_perm:[1,0,3,2] row_mask:0xf bank_mask:0xf bound_ctrl:1
	v_add_f32_dpp v142, v144, v142 quad_perm:[1,0,3,2] row_mask:0xf bank_mask:0xf bound_ctrl:1
	v_cndmask_b32_e64 v143, v142, v146, s[4:5]
	v_cndmask_b32_e64 v86, v146, v142, s[4:5]
	s_nop 1
	v_add_f32_dpp v86, v86, v143 quad_perm:[2,3,0,1] row_mask:0xf bank_mask:0xf bound_ctrl:1
	v_cndmask_b32_e64 v86, 0, v86, s[6:7]
	s_nop 1
	v_add_f32_dpp v86, v86, v86 row_ror:4 row_mask:0xf bank_mask:0xf bound_ctrl:1
	s_nop 1
	v_add_f32_dpp v86, v86, v86 row_ror:8 row_mask:0xf bank_mask:0xf bound_ctrl:1
	v_mov_b32_e32 v87, v86
	s_nop 1
	v_permlane16_swap_b32_e32 v86, v87
	v_add_f32_e32 v86, v86, v87
	v_mov_b32_e32 v87, v86
	s_nop 1
	v_permlane32_swap_b32 v86, v87
	v_add_f32_e32 v86, v86, v87
	v_mul_f32_e32 v93, v88, v86
	s_mov_b64 exec, s[8:9]
	ds_write_b32 v89, v93 offset:10240
	s_mov_b64 exec, -1
	s_waitcnt vmcnt(12) lgkmcnt(10)
	v_mul_f32_e32 v88, v128, v85
	v_mfma_f32_16x16x32_fp8_fp8 v[184:187], v[50:51], v[94:95], 0
	v_mfma_f32_16x16x32_fp8_fp8 v[188:191], v[54:55], v[94:95], 0
	v_mfma_f32_16x16x32_fp8_fp8 v[192:195], v[58:59], v[94:95], 0
	v_mfma_f32_16x16x32_fp8_fp8 v[196:199], v[62:63], v[94:95], 0
	v_mfma_f32_16x16x32_fp8_fp8 v[184:187], v[52:53], v[96:97], v[184:187]
	v_mfma_f32_16x16x32_fp8_fp8 v[188:191], v[56:57], v[96:97], v[188:191]
	v_mfma_f32_16x16x32_fp8_fp8 v[192:195], v[60:61], v[96:97], v[192:195]
	v_mfma_f32_16x16x32_fp8_fp8 v[196:199], v[64:65], v[96:97], v[196:199]
	v_lshl_add_u32 v145, v78, 10, v92
	global_load_dwordx4 v[50:53], v145, s[98:99]
	v_lshl_add_u32 v1, v79, 10, v92
	global_load_dwordx4 v[54:57], v1, s[98:99]
	v_lshl_add_u32 v145, v80, 10, v92
	global_load_dwordx4 v[58:61], v145, s[98:99]
	v_lshl_add_u32 v1, v81, 10, v92
	global_load_dwordx4 v[62:65], v1, s[98:99]
	ds_read_b32 v85, v90 offset:5632
	ds_read_b128 v[78:81], v91 offset:10752
	v_cndmask_b32_e64 v184, v185, v184, s[2:3]
	v_cndmask_b32_e64 v185, v187, v186, s[2:3]
	v_cndmask_b32_e64 v188, v189, v188, s[2:3]
	v_cndmask_b32_e64 v189, v191, v190, s[2:3]
	v_cndmask_b32_e64 v192, v193, v192, s[2:3]
	v_cndmask_b32_e64 v193, v195, v194, s[2:3]
	v_cndmask_b32_e64 v196, v197, v196, s[2:3]
	v_cndmask_b32_e64 v197, v199, v198, s[2:3]
	v_cndmask_b32_e64 v184, v185, v184, s[4:5]
	v_cndmask_b32_e64 v188, v189, v188, s[4:5]
	v_cndmask_b32_e64 v192, v193, v192, s[4:5]
	v_cndmask_b32_e64 v196, v197, v196, s[4:5]
	v_cndmask_b32_e64 v146, v188, v184, s[2:3]
	v_cndmask_b32_e64 v143, v184, v188, s[2:3]
	v_cndmask_b32_e64 v142, v196, v192, s[2:3]
	v_cndmask_b32_e64 v144, v192, v196, s[2:3]
	s_nop 0
	v_add_f32_dpp v146, v143, v146 quad_perm:[1,0,3,2] row_mask:0xf bank_mask:0xf bound_ctrl:1
	v_add_f32_dpp v142, v144, v142 quad_perm:[1,0,3,2] row_mask:0xf bank_mask:0xf bound_ctrl:1
	v_cndmask_b32_e64 v143, v142, v146, s[4:5]
	v_cndmask_b32_e64 v86, v146, v142, s[4:5]
	s_nop 1
	v_add_f32_dpp v86, v86, v143 quad_perm:[2,3,0,1] row_mask:0xf bank_mask:0xf bound_ctrl:1
	v_cndmask_b32_e64 v86, 0, v86, s[6:7]
	s_nop 1
	v_add_f32_dpp v86, v86, v86 row_ror:4 row_mask:0xf bank_mask:0xf bound_ctrl:1
	s_nop 1
	v_add_f32_dpp v86, v86, v86 row_ror:8 row_mask:0xf bank_mask:0xf bound_ctrl:1
	v_mov_b32_e32 v87, v86
	s_nop 1
	v_permlane16_swap_b32_e32 v86, v87
	v_add_f32_e32 v86, v86, v87
	v_mov_b32_e32 v87, v86
	s_nop 1
	v_permlane32_swap_b32 v86, v87
	v_add_f32_e32 v86, v86, v87
	v_mul_f32_e32 v93, v88, v86
	s_mov_b64 exec, s[8:9]
	ds_write_b32 v89, v93 offset:11776
	s_mov_b64 exec, -1
	v_mov_b32_e32 v89, v90
	s_mov_b32 s34, s35
	s_add_i32 s95, s95, 1
	s_cmp_eq_u32 s95, 32
	s_cbranch_scc0 .Lus_loop
	s_waitcnt vmcnt(0) lgkmcnt(0)
	s_waitcnt lgkmcnt(0)
	s_waitcnt vmcnt(4)
	ds_read2st64_b32 v[2:3], v178 offset0:2 offset1:3
	ds_read2st64_b32 v[4:5], v178 offset0:4 offset1:5
	s_mov_b32 s0, 0x3e6d3388
	s_waitcnt lgkmcnt(0)
	v_fma_f32 v1, |v4|, s0, 1.0
	v_rcp_f32_e32 v1, v1
	v_cmp_gt_f32_e32 vcc, 0, v4
	v_fmamk_f32 v6, v1, 0x3f07dc22, v210
	v_fmaak_f32 v6, v1, v6, 0x3f35f0e3
	v_fmaak_f32 v6, v1, v6, 0xbe11a98e
	v_fmaak_f32 v6, v1, v6, 0x3e027906
	v_mul_f32_e32 v1, v1, v6
	v_mul_f32_e32 v6, v4, v4
	v_mul_f32_e32 v6, 0xbf38aa3b, v6
	v_exp_f32_e32 v6, v6
	s_nop 0
	v_mul_f32_e32 v1, v6, v1
	v_mul_f32_e32 v6, v4, v1
	v_fma_f32 v1, -v4, v1, v4
	v_cndmask_b32_e32 v1, v1, v6, vcc
	v_mul_f32_e32 v1, v2, v1
	v_fma_f32 v2, |v5|, s0, 1.0
	v_rcp_f32_e32 v2, v2
	v_cmp_gt_f32_e32 vcc, 0, v5
	v_fmamk_f32 v4, v2, 0x3f07dc22, v210
	v_fmaak_f32 v4, v2, v4, 0x3f35f0e3
	v_fmaak_f32 v4, v2, v4, 0xbe11a98e
	v_fmaak_f32 v4, v2, v4, 0x3e027906
	v_mul_f32_e32 v2, v2, v4
	v_mul_f32_e32 v4, v5, v5
	v_mul_f32_e32 v4, 0xbf38aa3b, v4
	v_exp_f32_e32 v4, v4
	s_nop 0
	v_mul_f32_e32 v2, v4, v2
	v_mul_f32_e32 v4, v5, v2
	v_fma_f32 v2, -v5, v2, v5
	v_cndmask_b32_e32 v2, v2, v4, vcc
	v_mul_f32_e32 v2, v3, v2
	v_max_f32_e64 v3, |v1|, |v2|
	s_nop 1
	v_mov_b32_dpp v4, v3 quad_perm:[1,0,3,2] row_mask:0xf bank_mask:0xf bound_ctrl:1
	v_max_f32_e32 v4, v4, v4
	v_max_f32_e32 v3, v3, v4
	s_nop 1
	v_mov_b32_dpp v4, v3 quad_perm:[2,3,0,1] row_mask:0xf bank_mask:0xf bound_ctrl:1
	v_max_f32_e32 v4, v4, v4
	v_max_f32_e32 v3, v3, v4
	s_nop 1
	v_mov_b32_dpp v4, v3 row_half_mirror row_mask:0xf bank_mask:0xf bound_ctrl:1
	v_max_f32_e32 v4, v4, v4
	v_max_f32_e32 v3, v3, v4
	s_nop 1
	v_mov_b32_dpp v4, v3 row_mirror row_mask:0xf bank_mask:0xf bound_ctrl:1
	v_max_f32_e32 v4, v4, v4
	v_max_f32_e32 v3, v3, v4
	s_nop 0
	v_readlane_b32 s0, v3, 0
	v_readlane_b32 s1, v3, 16
	v_readlane_b32 s10, v3, 32
	v_readlane_b32 s11, v3, 48
	v_max_f32_e64 v3, s1, s1
	v_max_f32_e64 v4, s0, s0
	v_max_f32_e32 v3, v4, v3
	v_max_f32_e64 v4, s11, s11
	v_max_f32_e64 v5, s10, s10
	v_max_f32_e32 v4, v5, v4
	s_mov_b32 s0, 0xda24260
	v_max3_f32 v3, v3, v4, s0
	s_mov_b64 s[0:1], exec
	v_readlane_b32 s10, v254, 21
	v_readlane_b32 s11, v254, 22
	s_and_b64 s[10:11], s[0:1], s[10:11]
	s_mov_b64 exec, s[10:11]
	v_mul_f32_e32 v4, 0x3b888889, v3
	v_mov_b32_e32 v5, s93
	ds_write_b32 v5, v4 offset:14336
	s_or_b64 exec, exec, s[0:1]
	s_mov_b32 s10, 0x43700000
	v_div_scale_f32 v4, s[0:1], v3, v3, s10
	v_rcp_f32_e32 v5, v4
	s_mov_b32 s0, 0x7020c0c
	v_fma_f32 v6, -v4, v5, 1.0
	v_fmac_f32_e32 v5, v6, v5
	v_div_scale_f32 v6, vcc, s10, v3, s10
	v_mul_f32_e32 v7, v6, v5
	v_fma_f32 v8, -v4, v7, v6
	v_fmac_f32_e32 v7, v8, v5
	v_fma_f32 v4, -v4, v7, v6
	v_div_fmas_f32 v4, v4, v5, v7
	v_div_fixup_f32 v3, v4, v3, s10
	v_mul_f32_e32 v4, v3, v1
	v_mul_f32_e32 v5, v3, v2
	v_mov_b32_e32 v6, v155
	v_cvt_pk_fp8_f32 v6, v4, v5
	v_cvt_pk_f32_fp8_e32 v[4:5], v6
	v_fma_f32 v1, v3, v1, -v4
	v_fma_f32 v2, v3, v2, -v5
	v_mov_b32_e32 v4, v155
	v_cvt_pk_fp8_f32 v4, v1, v2
	ds_read2st64_b32 v[2:3], v178 offset1:1
	v_lshlrev_b32_e32 v1, 16, v6
	v_and_b32_e32 v1, 0xff0000, v1
	v_lshlrev_b32_e32 v5, 24, v4
	v_lshlrev_b32_e32 v4, 16, v4
	s_waitcnt lgkmcnt(0)
	v_or3_b32 v1, v2, v1, v5
	v_lshlrev_b32_e32 v2, 8, v6
	v_perm_b32 v2, v4, v2, s0
	v_or_b32_e32 v2, v2, v3
	ds_write2st64_b32 v178, v1, v2 offset0:2 offset1:3
	ds_read2st64_b32 v[2:3], v178 offset0:8 offset1:9
	ds_read2st64_b32 v[4:5], v178 offset0:10 offset1:11
	s_mov_b32 s0, 0x3e6d3388
	s_waitcnt lgkmcnt(0)
	v_fma_f32 v1, |v4|, s0, 1.0
	v_rcp_f32_e32 v1, v1
	v_cmp_gt_f32_e32 vcc, 0, v4
	v_fmamk_f32 v6, v1, 0x3f07dc22, v210
	v_fmaak_f32 v6, v1, v6, 0x3f35f0e3
	v_fmaak_f32 v6, v1, v6, 0xbe11a98e
	v_fmaak_f32 v6, v1, v6, 0x3e027906
	v_mul_f32_e32 v1, v1, v6
	v_mul_f32_e32 v6, v4, v4
	v_mul_f32_e32 v6, 0xbf38aa3b, v6
	v_exp_f32_e32 v6, v6
	s_nop 0
	v_mul_f32_e32 v1, v6, v1
	v_mul_f32_e32 v6, v4, v1
	v_fma_f32 v1, -v4, v1, v4
	v_cndmask_b32_e32 v1, v1, v6, vcc
	v_mul_f32_e32 v1, v2, v1
	v_fma_f32 v2, |v5|, s0, 1.0
	v_rcp_f32_e32 v2, v2
	v_cmp_gt_f32_e32 vcc, 0, v5
	v_fmamk_f32 v4, v2, 0x3f07dc22, v210
	v_fmaak_f32 v4, v2, v4, 0x3f35f0e3
	v_fmaak_f32 v4, v2, v4, 0xbe11a98e
	v_fmaak_f32 v4, v2, v4, 0x3e027906
	v_mul_f32_e32 v2, v2, v4
	v_mul_f32_e32 v4, v5, v5
	v_mul_f32_e32 v4, 0xbf38aa3b, v4
	v_exp_f32_e32 v4, v4
	s_nop 0
	v_mul_f32_e32 v2, v4, v2
	v_mul_f32_e32 v4, v5, v2
	v_fma_f32 v2, -v5, v2, v5
	v_cndmask_b32_e32 v2, v2, v4, vcc
	v_mul_f32_e32 v2, v3, v2
	v_max_f32_e64 v3, |v1|, |v2|
	s_nop 1
	v_mov_b32_dpp v4, v3 quad_perm:[1,0,3,2] row_mask:0xf bank_mask:0xf bound_ctrl:1
	v_max_f32_e32 v4, v4, v4
	v_max_f32_e32 v3, v3, v4
	s_nop 1
	v_mov_b32_dpp v4, v3 quad_perm:[2,3,0,1] row_mask:0xf bank_mask:0xf bound_ctrl:1
	v_max_f32_e32 v4, v4, v4
	v_max_f32_e32 v3, v3, v4
	s_nop 1
	v_mov_b32_dpp v4, v3 row_half_mirror row_mask:0xf bank_mask:0xf bound_ctrl:1
	v_max_f32_e32 v4, v4, v4
	v_max_f32_e32 v3, v3, v4
	s_nop 1
	v_mov_b32_dpp v4, v3 row_mirror row_mask:0xf bank_mask:0xf bound_ctrl:1
	v_max_f32_e32 v4, v4, v4
	v_max_f32_e32 v3, v3, v4
	s_nop 0
	v_readlane_b32 s0, v3, 0
	v_readlane_b32 s1, v3, 16
	v_readlane_b32 s10, v3, 32
	v_readlane_b32 s11, v3, 48
	v_max_f32_e64 v3, s1, s1
	v_max_f32_e64 v4, s0, s0
	v_max_f32_e32 v3, v4, v3
	v_max_f32_e64 v4, s11, s11
	v_max_f32_e64 v5, s10, s10
	v_max_f32_e32 v4, v5, v4
	s_mov_b32 s0, 0xda24260
	v_max3_f32 v3, v3, v4, s0
	s_mov_b64 s[0:1], exec
	v_readlane_b32 s10, v254, 21
	v_readlane_b32 s11, v254, 22
	s_and_b64 s[10:11], s[0:1], s[10:11]
	s_mov_b64 exec, s[10:11]
	v_mul_f32_e32 v4, 0x3b888889, v3
	v_mov_b32_e32 v5, s93
	ds_write_b32 v5, v4 offset:14340
	s_or_b64 exec, exec, s[0:1]
	s_mov_b32 s10, 0x43700000
	v_div_scale_f32 v4, s[0:1], v3, v3, s10
	v_rcp_f32_e32 v5, v4
	s_mov_b32 s0, 0x7020c0c
	v_fma_f32 v6, -v4, v5, 1.0
	v_fmac_f32_e32 v5, v6, v5
	v_div_scale_f32 v6, vcc, s10, v3, s10
	v_mul_f32_e32 v7, v6, v5
	v_fma_f32 v8, -v4, v7, v6
	v_fmac_f32_e32 v7, v8, v5
	v_fma_f32 v4, -v4, v7, v6
	v_div_fmas_f32 v4, v4, v5, v7
	v_div_fixup_f32 v3, v4, v3, s10
	v_mul_f32_e32 v4, v3, v1
	v_mul_f32_e32 v5, v3, v2
	v_mov_b32_e32 v6, v155
	v_cvt_pk_fp8_f32 v6, v4, v5
	v_cvt_pk_f32_fp8_e32 v[4:5], v6
	v_fma_f32 v1, v3, v1, -v4
	v_fma_f32 v2, v3, v2, -v5
	v_mov_b32_e32 v4, v155
	v_cvt_pk_fp8_f32 v4, v1, v2
	ds_read2st64_b32 v[2:3], v178 offset0:6 offset1:7
	v_lshlrev_b32_e32 v1, 16, v6
	v_and_b32_e32 v1, 0xff0000, v1
	v_lshlrev_b32_e32 v5, 24, v4
	v_lshlrev_b32_e32 v4, 16, v4
	s_waitcnt lgkmcnt(0)
	v_or3_b32 v1, v2, v1, v5
	v_lshlrev_b32_e32 v2, 8, v6
	v_perm_b32 v2, v4, v2, s0
	v_or_b32_e32 v2, v2, v3
	ds_write2st64_b32 v178, v1, v2 offset0:8 offset1:9
	ds_read2st64_b32 v[2:3], v178 offset0:14 offset1:15
	ds_read2st64_b32 v[4:5], v178 offset0:16 offset1:17
	s_mov_b32 s0, 0x3e6d3388
	s_waitcnt lgkmcnt(0)
	v_fma_f32 v1, |v4|, s0, 1.0
	v_rcp_f32_e32 v1, v1
	v_cmp_gt_f32_e32 vcc, 0, v4
	v_fmamk_f32 v6, v1, 0x3f07dc22, v210
	v_fmaak_f32 v6, v1, v6, 0x3f35f0e3
	v_fmaak_f32 v6, v1, v6, 0xbe11a98e
	v_fmaak_f32 v6, v1, v6, 0x3e027906
	v_mul_f32_e32 v1, v1, v6
	v_mul_f32_e32 v6, v4, v4
	v_mul_f32_e32 v6, 0xbf38aa3b, v6
	v_exp_f32_e32 v6, v6
	s_nop 0
	v_mul_f32_e32 v1, v6, v1
	v_mul_f32_e32 v6, v4, v1
	v_fma_f32 v1, -v4, v1, v4
	v_cndmask_b32_e32 v1, v1, v6, vcc
	v_mul_f32_e32 v1, v2, v1
	v_fma_f32 v2, |v5|, s0, 1.0
	v_rcp_f32_e32 v2, v2
	v_cmp_gt_f32_e32 vcc, 0, v5
	v_fmamk_f32 v4, v2, 0x3f07dc22, v210
	v_fmaak_f32 v4, v2, v4, 0x3f35f0e3
	v_fmaak_f32 v4, v2, v4, 0xbe11a98e
	v_fmaak_f32 v4, v2, v4, 0x3e027906
	v_mul_f32_e32 v2, v2, v4
	v_mul_f32_e32 v4, v5, v5
	v_mul_f32_e32 v4, 0xbf38aa3b, v4
	v_exp_f32_e32 v4, v4
	s_nop 0
	v_mul_f32_e32 v2, v4, v2
	v_mul_f32_e32 v4, v5, v2
	v_fma_f32 v2, -v5, v2, v5
	v_cndmask_b32_e32 v2, v2, v4, vcc
	v_mul_f32_e32 v2, v3, v2
	v_max_f32_e64 v3, |v1|, |v2|
	s_nop 1
	v_mov_b32_dpp v4, v3 quad_perm:[1,0,3,2] row_mask:0xf bank_mask:0xf bound_ctrl:1
	v_max_f32_e32 v4, v4, v4
	v_max_f32_e32 v3, v3, v4
	s_nop 1
	v_mov_b32_dpp v4, v3 quad_perm:[2,3,0,1] row_mask:0xf bank_mask:0xf bound_ctrl:1
	v_max_f32_e32 v4, v4, v4
	v_max_f32_e32 v3, v3, v4
	s_nop 1
	v_mov_b32_dpp v4, v3 row_half_mirror row_mask:0xf bank_mask:0xf bound_ctrl:1
	v_max_f32_e32 v4, v4, v4
	v_max_f32_e32 v3, v3, v4
	s_nop 1
	v_mov_b32_dpp v4, v3 row_mirror row_mask:0xf bank_mask:0xf bound_ctrl:1
	v_max_f32_e32 v4, v4, v4
	v_max_f32_e32 v3, v3, v4
	s_nop 0
	v_readlane_b32 s0, v3, 0
	v_readlane_b32 s1, v3, 16
	v_readlane_b32 s10, v3, 32
	v_readlane_b32 s11, v3, 48
	v_max_f32_e64 v3, s1, s1
	v_max_f32_e64 v4, s0, s0
	v_max_f32_e32 v3, v4, v3
	v_max_f32_e64 v4, s11, s11
	v_max_f32_e64 v5, s10, s10
	v_max_f32_e32 v4, v5, v4
	s_mov_b32 s0, 0xda24260
	v_max3_f32 v3, v3, v4, s0
	s_mov_b64 s[0:1], exec
	v_readlane_b32 s10, v254, 21
	v_readlane_b32 s11, v254, 22
	s_and_b64 s[10:11], s[0:1], s[10:11]
	s_mov_b64 exec, s[10:11]
	v_mul_f32_e32 v4, 0x3b888889, v3
	v_mov_b32_e32 v5, s93
	ds_write_b32 v5, v4 offset:14344
	s_or_b64 exec, exec, s[0:1]
	s_mov_b32 s10, 0x43700000
	v_div_scale_f32 v4, s[0:1], v3, v3, s10
	v_rcp_f32_e32 v5, v4
	s_mov_b32 s0, 0x7020c0c
	v_fma_f32 v6, -v4, v5, 1.0
	v_fmac_f32_e32 v5, v6, v5
	v_div_scale_f32 v6, vcc, s10, v3, s10
	v_mul_f32_e32 v7, v6, v5
	v_fma_f32 v8, -v4, v7, v6
	v_fmac_f32_e32 v7, v8, v5
	v_fma_f32 v4, -v4, v7, v6
	v_div_fmas_f32 v4, v4, v5, v7
	v_div_fixup_f32 v3, v4, v3, s10
	v_mul_f32_e32 v4, v3, v1
	v_mul_f32_e32 v5, v3, v2
	v_mov_b32_e32 v6, v155
	v_cvt_pk_fp8_f32 v6, v4, v5
	v_cvt_pk_f32_fp8_e32 v[4:5], v6
	v_fma_f32 v1, v3, v1, -v4
	v_fma_f32 v2, v3, v2, -v5
	v_mov_b32_e32 v4, v155
	v_cvt_pk_fp8_f32 v4, v1, v2
	ds_read2st64_b32 v[2:3], v178 offset0:12 offset1:13
	v_lshlrev_b32_e32 v1, 16, v6
	v_and_b32_e32 v1, 0xff0000, v1
	v_lshlrev_b32_e32 v5, 24, v4
	v_lshlrev_b32_e32 v4, 16, v4
	s_waitcnt lgkmcnt(0)
	v_or3_b32 v1, v2, v1, v5
	v_lshlrev_b32_e32 v2, 8, v6
	v_perm_b32 v2, v4, v2, s0
	v_or_b32_e32 v2, v2, v3
	ds_write2st64_b32 v178, v1, v2 offset0:14 offset1:15
	ds_read2st64_b32 v[2:3], v178 offset0:20 offset1:21
	ds_read2st64_b32 v[4:5], v178 offset0:22 offset1:23
	s_mov_b32 s0, 0x3e6d3388
	s_waitcnt lgkmcnt(0)
	v_fma_f32 v1, |v4|, s0, 1.0
	v_rcp_f32_e32 v1, v1
	v_cmp_gt_f32_e32 vcc, 0, v4
	v_fmamk_f32 v6, v1, 0x3f07dc22, v210
	v_fmaak_f32 v6, v1, v6, 0x3f35f0e3
	v_fmaak_f32 v6, v1, v6, 0xbe11a98e
	v_fmaak_f32 v6, v1, v6, 0x3e027906
	v_mul_f32_e32 v1, v1, v6
	v_mul_f32_e32 v6, v4, v4
	v_mul_f32_e32 v6, 0xbf38aa3b, v6
	v_exp_f32_e32 v6, v6
	s_nop 0
	v_mul_f32_e32 v1, v6, v1
	v_mul_f32_e32 v6, v4, v1
	v_fma_f32 v1, -v4, v1, v4
	v_cndmask_b32_e32 v1, v1, v6, vcc
	v_mul_f32_e32 v1, v2, v1
	v_fma_f32 v2, |v5|, s0, 1.0
	v_rcp_f32_e32 v2, v2
	v_cmp_gt_f32_e32 vcc, 0, v5
	v_fmamk_f32 v4, v2, 0x3f07dc22, v210
	v_fmaak_f32 v4, v2, v4, 0x3f35f0e3
	v_fmaak_f32 v4, v2, v4, 0xbe11a98e
	v_fmaak_f32 v4, v2, v4, 0x3e027906
	v_mul_f32_e32 v2, v2, v4
	v_mul_f32_e32 v4, v5, v5
	v_mul_f32_e32 v4, 0xbf38aa3b, v4
	v_exp_f32_e32 v4, v4
	s_nop 0
	v_mul_f32_e32 v2, v4, v2
	v_mul_f32_e32 v4, v5, v2
	v_fma_f32 v2, -v5, v2, v5
	v_cndmask_b32_e32 v2, v2, v4, vcc
	v_mul_f32_e32 v2, v3, v2
	v_max_f32_e64 v3, |v1|, |v2|
	s_nop 1
	v_mov_b32_dpp v4, v3 quad_perm:[1,0,3,2] row_mask:0xf bank_mask:0xf bound_ctrl:1
	v_max_f32_e32 v4, v4, v4
	v_max_f32_e32 v3, v3, v4
	s_nop 1
	v_mov_b32_dpp v4, v3 quad_perm:[2,3,0,1] row_mask:0xf bank_mask:0xf bound_ctrl:1
	v_max_f32_e32 v4, v4, v4
	v_max_f32_e32 v3, v3, v4
	s_nop 1
	v_mov_b32_dpp v4, v3 row_half_mirror row_mask:0xf bank_mask:0xf bound_ctrl:1
	v_max_f32_e32 v4, v4, v4
	v_max_f32_e32 v3, v3, v4
	s_nop 1
	v_mov_b32_dpp v4, v3 row_mirror row_mask:0xf bank_mask:0xf bound_ctrl:1
	v_max_f32_e32 v4, v4, v4
	v_max_f32_e32 v3, v3, v4
	s_nop 0
	v_readlane_b32 s0, v3, 0
	v_readlane_b32 s1, v3, 16
	v_readlane_b32 s10, v3, 32
	v_readlane_b32 s11, v3, 48
	v_max_f32_e64 v3, s1, s1
	v_max_f32_e64 v4, s0, s0
	v_max_f32_e32 v3, v4, v3
	v_max_f32_e64 v4, s11, s11
	v_max_f32_e64 v5, s10, s10
	v_max_f32_e32 v4, v5, v4
	s_mov_b32 s0, 0xda24260
	v_max3_f32 v3, v3, v4, s0
	s_mov_b64 s[0:1], exec
	v_readlane_b32 s10, v254, 21
	v_readlane_b32 s11, v254, 22
	s_and_b64 s[10:11], s[0:1], s[10:11]
	s_mov_b64 exec, s[10:11]
	v_mul_f32_e32 v4, 0x3b888889, v3
	v_mov_b32_e32 v5, s93
	ds_write_b32 v5, v4 offset:14348
	s_or_b64 exec, exec, s[0:1]
	s_mov_b32 s10, 0x43700000
	v_div_scale_f32 v4, s[0:1], v3, v3, s10
	v_rcp_f32_e32 v5, v4
	s_mov_b32 s0, 0x7020c0c
	v_fma_f32 v6, -v4, v5, 1.0
	v_fmac_f32_e32 v5, v6, v5
	v_div_scale_f32 v6, vcc, s10, v3, s10
	v_mul_f32_e32 v7, v6, v5
	v_fma_f32 v8, -v4, v7, v6
	v_fmac_f32_e32 v7, v8, v5
	v_fma_f32 v4, -v4, v7, v6
	v_div_fmas_f32 v4, v4, v5, v7
	v_div_fixup_f32 v3, v4, v3, s10
	v_mul_f32_e32 v4, v3, v1
	v_mul_f32_e32 v5, v3, v2
	v_mov_b32_e32 v6, v155
	v_cvt_pk_fp8_f32 v6, v4, v5
	v_cvt_pk_f32_fp8_e32 v[4:5], v6
	v_fma_f32 v1, v3, v1, -v4
	v_fma_f32 v2, v3, v2, -v5
	v_mov_b32_e32 v4, v155
	v_cvt_pk_fp8_f32 v4, v1, v2
	ds_read2st64_b32 v[2:3], v178 offset0:18 offset1:19
	v_lshlrev_b32_e32 v1, 16, v6
	v_and_b32_e32 v1, 0xff0000, v1
	v_lshlrev_b32_e32 v5, 24, v4
	v_lshlrev_b32_e32 v4, 16, v4
	s_waitcnt lgkmcnt(0)
	v_or3_b32 v1, v2, v1, v5
	v_lshlrev_b32_e32 v2, 8, v6
	v_perm_b32 v2, v4, v2, s0
	v_or_b32_e32 v2, v2, v3
	ds_write2st64_b32 v178, v1, v2 offset0:20 offset1:21
	ds_read2st64_b32 v[2:3], v178 offset0:26 offset1:27
	ds_read2st64_b32 v[4:5], v178 offset0:28 offset1:29
	s_mov_b32 s0, 0x3e6d3388
	s_waitcnt lgkmcnt(0)
	v_fma_f32 v1, |v4|, s0, 1.0
	v_rcp_f32_e32 v1, v1
	v_cmp_gt_f32_e32 vcc, 0, v4
	v_fmamk_f32 v6, v1, 0x3f07dc22, v210
	v_fmaak_f32 v6, v1, v6, 0x3f35f0e3
	v_fmaak_f32 v6, v1, v6, 0xbe11a98e
	v_fmaak_f32 v6, v1, v6, 0x3e027906
	v_mul_f32_e32 v1, v1, v6
	v_mul_f32_e32 v6, v4, v4
	v_mul_f32_e32 v6, 0xbf38aa3b, v6
	v_exp_f32_e32 v6, v6
	s_nop 0
	v_mul_f32_e32 v1, v6, v1
	v_mul_f32_e32 v6, v4, v1
	v_fma_f32 v1, -v4, v1, v4
	v_cndmask_b32_e32 v1, v1, v6, vcc
	v_mul_f32_e32 v1, v2, v1
	v_fma_f32 v2, |v5|, s0, 1.0
	v_rcp_f32_e32 v2, v2
	v_cmp_gt_f32_e32 vcc, 0, v5
	v_fmamk_f32 v4, v2, 0x3f07dc22, v210
	v_fmaak_f32 v4, v2, v4, 0x3f35f0e3
	v_fmaak_f32 v4, v2, v4, 0xbe11a98e
	v_fmaak_f32 v4, v2, v4, 0x3e027906
	v_mul_f32_e32 v2, v2, v4
	v_mul_f32_e32 v4, v5, v5
	v_mul_f32_e32 v4, 0xbf38aa3b, v4
	v_exp_f32_e32 v4, v4
	s_nop 0
	v_mul_f32_e32 v2, v4, v2
	v_mul_f32_e32 v4, v5, v2
	v_fma_f32 v2, -v5, v2, v5
	v_cndmask_b32_e32 v2, v2, v4, vcc
	v_mul_f32_e32 v2, v3, v2
	v_max_f32_e64 v3, |v1|, |v2|
	s_nop 1
	v_mov_b32_dpp v4, v3 quad_perm:[1,0,3,2] row_mask:0xf bank_mask:0xf bound_ctrl:1
	v_max_f32_e32 v4, v4, v4
	v_max_f32_e32 v3, v3, v4
	s_nop 1
	v_mov_b32_dpp v4, v3 quad_perm:[2,3,0,1] row_mask:0xf bank_mask:0xf bound_ctrl:1
	v_max_f32_e32 v4, v4, v4
	v_max_f32_e32 v3, v3, v4
	s_nop 1
	v_mov_b32_dpp v4, v3 row_half_mirror row_mask:0xf bank_mask:0xf bound_ctrl:1
	v_max_f32_e32 v4, v4, v4
	v_max_f32_e32 v3, v3, v4
	s_nop 1
	v_mov_b32_dpp v4, v3 row_mirror row_mask:0xf bank_mask:0xf bound_ctrl:1
	v_max_f32_e32 v4, v4, v4
	v_max_f32_e32 v3, v3, v4
	s_nop 0
	v_readlane_b32 s0, v3, 0
	v_readlane_b32 s1, v3, 16
	v_readlane_b32 s10, v3, 32
	v_readlane_b32 s11, v3, 48
	v_max_f32_e64 v3, s1, s1
	v_max_f32_e64 v4, s0, s0
	v_max_f32_e32 v3, v4, v3
	v_max_f32_e64 v4, s11, s11
	v_max_f32_e64 v5, s10, s10
	v_max_f32_e32 v4, v5, v4
	s_mov_b32 s0, 0xda24260
	v_max3_f32 v3, v3, v4, s0
	s_mov_b64 s[0:1], exec
	v_readlane_b32 s10, v254, 21
	v_readlane_b32 s11, v254, 22
	s_and_b64 s[10:11], s[0:1], s[10:11]
	s_mov_b64 exec, s[10:11]
	v_mul_f32_e32 v4, 0x3b888889, v3
	v_mov_b32_e32 v5, s93
	ds_write_b32 v5, v4 offset:14352
	s_or_b64 exec, exec, s[0:1]
	s_mov_b32 s10, 0x43700000
	v_div_scale_f32 v4, s[0:1], v3, v3, s10
	v_rcp_f32_e32 v5, v4
	s_mov_b32 s0, 0x7020c0c
	v_fma_f32 v6, -v4, v5, 1.0
	v_fmac_f32_e32 v5, v6, v5
	v_div_scale_f32 v6, vcc, s10, v3, s10
	v_mul_f32_e32 v7, v6, v5
	v_fma_f32 v8, -v4, v7, v6
	v_fmac_f32_e32 v7, v8, v5
	v_fma_f32 v4, -v4, v7, v6
	v_div_fmas_f32 v4, v4, v5, v7
	v_div_fixup_f32 v3, v4, v3, s10
	v_mul_f32_e32 v4, v3, v1
	v_mul_f32_e32 v5, v3, v2
	v_mov_b32_e32 v6, v155
	v_cvt_pk_fp8_f32 v6, v4, v5
	v_cvt_pk_f32_fp8_e32 v[4:5], v6
	v_fma_f32 v1, v3, v1, -v4
	v_fma_f32 v2, v3, v2, -v5
	v_mov_b32_e32 v4, v155
	v_cvt_pk_fp8_f32 v4, v1, v2
	ds_read2st64_b32 v[2:3], v178 offset0:24 offset1:25
	v_lshlrev_b32_e32 v1, 16, v6
	v_and_b32_e32 v1, 0xff0000, v1
	v_lshlrev_b32_e32 v5, 24, v4
	v_lshlrev_b32_e32 v4, 16, v4
	s_waitcnt lgkmcnt(0)
	v_or3_b32 v1, v2, v1, v5
	v_lshlrev_b32_e32 v2, 8, v6
	v_perm_b32 v2, v4, v2, s0
	v_or_b32_e32 v2, v2, v3
	ds_write2st64_b32 v178, v1, v2 offset0:26 offset1:27
	ds_read2st64_b32 v[2:3], v178 offset0:32 offset1:33
	ds_read2st64_b32 v[4:5], v178 offset0:34 offset1:35
	s_mov_b32 s0, 0x3e6d3388
	s_waitcnt lgkmcnt(0)
	v_fma_f32 v1, |v4|, s0, 1.0
	v_rcp_f32_e32 v1, v1
	v_cmp_gt_f32_e32 vcc, 0, v4
	v_fmamk_f32 v6, v1, 0x3f07dc22, v210
	v_fmaak_f32 v6, v1, v6, 0x3f35f0e3
	v_fmaak_f32 v6, v1, v6, 0xbe11a98e
	v_fmaak_f32 v6, v1, v6, 0x3e027906
	v_mul_f32_e32 v1, v1, v6
	v_mul_f32_e32 v6, v4, v4
	v_mul_f32_e32 v6, 0xbf38aa3b, v6
	v_exp_f32_e32 v6, v6
	s_nop 0
	v_mul_f32_e32 v1, v6, v1
	v_mul_f32_e32 v6, v4, v1
	v_fma_f32 v1, -v4, v1, v4
	v_cndmask_b32_e32 v1, v1, v6, vcc
	v_mul_f32_e32 v1, v2, v1
	v_fma_f32 v2, |v5|, s0, 1.0
	v_rcp_f32_e32 v2, v2
	v_cmp_gt_f32_e32 vcc, 0, v5
	v_fmamk_f32 v4, v2, 0x3f07dc22, v210
	v_fmaak_f32 v4, v2, v4, 0x3f35f0e3
	v_fmaak_f32 v4, v2, v4, 0xbe11a98e
	v_fmaak_f32 v4, v2, v4, 0x3e027906
	v_mul_f32_e32 v2, v2, v4
	v_mul_f32_e32 v4, v5, v5
	v_mul_f32_e32 v4, 0xbf38aa3b, v4
	v_exp_f32_e32 v4, v4
	s_nop 0
	v_mul_f32_e32 v2, v4, v2
	v_mul_f32_e32 v4, v5, v2
	v_fma_f32 v2, -v5, v2, v5
	v_cndmask_b32_e32 v2, v2, v4, vcc
	v_mul_f32_e32 v2, v3, v2
	v_max_f32_e64 v3, |v1|, |v2|
	s_nop 1
	v_mov_b32_dpp v4, v3 quad_perm:[1,0,3,2] row_mask:0xf bank_mask:0xf bound_ctrl:1
	v_max_f32_e32 v4, v4, v4
	v_max_f32_e32 v3, v3, v4
	s_nop 1
	v_mov_b32_dpp v4, v3 quad_perm:[2,3,0,1] row_mask:0xf bank_mask:0xf bound_ctrl:1
	v_max_f32_e32 v4, v4, v4
	v_max_f32_e32 v3, v3, v4
	s_nop 1
	v_mov_b32_dpp v4, v3 row_half_mirror row_mask:0xf bank_mask:0xf bound_ctrl:1
	v_max_f32_e32 v4, v4, v4
	v_max_f32_e32 v3, v3, v4
	s_nop 1
	v_mov_b32_dpp v4, v3 row_mirror row_mask:0xf bank_mask:0xf bound_ctrl:1
	v_max_f32_e32 v4, v4, v4
	v_max_f32_e32 v3, v3, v4
	s_nop 0
	v_readlane_b32 s0, v3, 0
	v_readlane_b32 s1, v3, 16
	v_readlane_b32 s10, v3, 32
	v_readlane_b32 s11, v3, 48
	v_max_f32_e64 v3, s1, s1
	v_max_f32_e64 v4, s0, s0
	v_max_f32_e32 v3, v4, v3
	v_max_f32_e64 v4, s11, s11
	v_max_f32_e64 v5, s10, s10
	v_max_f32_e32 v4, v5, v4
	s_mov_b32 s0, 0xda24260
	v_max3_f32 v3, v3, v4, s0
	s_mov_b64 s[0:1], exec
	v_readlane_b32 s10, v254, 21
	v_readlane_b32 s11, v254, 22
	s_and_b64 s[10:11], s[0:1], s[10:11]
	s_mov_b64 exec, s[10:11]
	v_mul_f32_e32 v4, 0x3b888889, v3
	v_mov_b32_e32 v5, s93
	ds_write_b32 v5, v4 offset:14356
	s_or_b64 exec, exec, s[0:1]
	s_mov_b32 s10, 0x43700000
	v_div_scale_f32 v4, s[0:1], v3, v3, s10
	v_rcp_f32_e32 v5, v4
	s_mov_b32 s0, 0x7020c0c
	v_fma_f32 v6, -v4, v5, 1.0
	v_fmac_f32_e32 v5, v6, v5
	v_div_scale_f32 v6, vcc, s10, v3, s10
	v_mul_f32_e32 v7, v6, v5
	v_fma_f32 v8, -v4, v7, v6
	v_fmac_f32_e32 v7, v8, v5
	v_fma_f32 v4, -v4, v7, v6
	v_div_fmas_f32 v4, v4, v5, v7
	v_div_fixup_f32 v3, v4, v3, s10
	v_mul_f32_e32 v4, v3, v1
	v_mul_f32_e32 v5, v3, v2
	v_mov_b32_e32 v6, v155
	v_cvt_pk_fp8_f32 v6, v4, v5
	v_cvt_pk_f32_fp8_e32 v[4:5], v6
	v_fma_f32 v1, v3, v1, -v4
	v_fma_f32 v2, v3, v2, -v5
	v_mov_b32_e32 v4, v155
	v_cvt_pk_fp8_f32 v4, v1, v2
	ds_read2st64_b32 v[2:3], v178 offset0:30 offset1:31
	v_lshlrev_b32_e32 v1, 16, v6
	v_and_b32_e32 v1, 0xff0000, v1
	v_lshlrev_b32_e32 v5, 24, v4
	v_lshlrev_b32_e32 v4, 16, v4
	s_waitcnt lgkmcnt(0)
	v_or3_b32 v1, v2, v1, v5
	v_lshlrev_b32_e32 v2, 8, v6
	v_perm_b32 v2, v4, v2, s0
	v_or_b32_e32 v2, v2, v3
	ds_write2st64_b32 v178, v1, v2 offset0:32 offset1:33
	ds_read2st64_b32 v[2:3], v178 offset0:38 offset1:39
	ds_read2st64_b32 v[4:5], v178 offset0:40 offset1:41
	s_mov_b32 s0, 0x3e6d3388
	s_waitcnt lgkmcnt(0)
	v_fma_f32 v1, |v4|, s0, 1.0
	v_rcp_f32_e32 v1, v1
	v_cmp_gt_f32_e32 vcc, 0, v4
	v_fmamk_f32 v6, v1, 0x3f07dc22, v210
	v_fmaak_f32 v6, v1, v6, 0x3f35f0e3
	v_fmaak_f32 v6, v1, v6, 0xbe11a98e
	v_fmaak_f32 v6, v1, v6, 0x3e027906
	v_mul_f32_e32 v1, v1, v6
	v_mul_f32_e32 v6, v4, v4
	v_mul_f32_e32 v6, 0xbf38aa3b, v6
	v_exp_f32_e32 v6, v6
	s_nop 0
	v_mul_f32_e32 v1, v6, v1
	v_mul_f32_e32 v6, v4, v1
	v_fma_f32 v1, -v4, v1, v4
	v_cndmask_b32_e32 v1, v1, v6, vcc
	v_mul_f32_e32 v1, v2, v1
	v_fma_f32 v2, |v5|, s0, 1.0
	v_rcp_f32_e32 v2, v2
	v_cmp_gt_f32_e32 vcc, 0, v5
	v_fmamk_f32 v4, v2, 0x3f07dc22, v210
	v_fmaak_f32 v4, v2, v4, 0x3f35f0e3
	v_fmaak_f32 v4, v2, v4, 0xbe11a98e
	v_fmaak_f32 v4, v2, v4, 0x3e027906
	v_mul_f32_e32 v2, v2, v4
	v_mul_f32_e32 v4, v5, v5
	v_mul_f32_e32 v4, 0xbf38aa3b, v4
	v_exp_f32_e32 v4, v4
	s_nop 0
	v_mul_f32_e32 v2, v4, v2
	v_mul_f32_e32 v4, v5, v2
	v_fma_f32 v2, -v5, v2, v5
	v_cndmask_b32_e32 v2, v2, v4, vcc
	v_mul_f32_e32 v2, v3, v2
	v_max_f32_e64 v3, |v1|, |v2|
	s_nop 1
	v_mov_b32_dpp v4, v3 quad_perm:[1,0,3,2] row_mask:0xf bank_mask:0xf bound_ctrl:1
	v_max_f32_e32 v4, v4, v4
	v_max_f32_e32 v3, v3, v4
	s_nop 1
	v_mov_b32_dpp v4, v3 quad_perm:[2,3,0,1] row_mask:0xf bank_mask:0xf bound_ctrl:1
	v_max_f32_e32 v4, v4, v4
	v_max_f32_e32 v3, v3, v4
	s_nop 1
	v_mov_b32_dpp v4, v3 row_half_mirror row_mask:0xf bank_mask:0xf bound_ctrl:1
	v_max_f32_e32 v4, v4, v4
	v_max_f32_e32 v3, v3, v4
	s_nop 1
	v_mov_b32_dpp v4, v3 row_mirror row_mask:0xf bank_mask:0xf bound_ctrl:1
	v_max_f32_e32 v4, v4, v4
	v_max_f32_e32 v3, v3, v4
	s_nop 0
	v_readlane_b32 s0, v3, 0
	v_readlane_b32 s1, v3, 16
	v_readlane_b32 s10, v3, 32
	v_readlane_b32 s11, v3, 48
	v_max_f32_e64 v3, s1, s1
	v_max_f32_e64 v4, s0, s0
	v_max_f32_e32 v3, v4, v3
	v_max_f32_e64 v4, s11, s11
	v_max_f32_e64 v5, s10, s10
	v_max_f32_e32 v4, v5, v4
	s_mov_b32 s0, 0xda24260
	v_max3_f32 v3, v3, v4, s0
	s_mov_b64 s[0:1], exec
	v_readlane_b32 s10, v254, 21
	v_readlane_b32 s11, v254, 22
	s_and_b64 s[10:11], s[0:1], s[10:11]
	s_mov_b64 exec, s[10:11]
	v_mul_f32_e32 v4, 0x3b888889, v3
	v_mov_b32_e32 v5, s93
	ds_write_b32 v5, v4 offset:14360
	s_or_b64 exec, exec, s[0:1]
	s_mov_b32 s10, 0x43700000
	v_div_scale_f32 v4, s[0:1], v3, v3, s10
	v_rcp_f32_e32 v5, v4
	s_mov_b32 s0, 0x7020c0c
	v_fma_f32 v6, -v4, v5, 1.0
	v_fmac_f32_e32 v5, v6, v5
	v_div_scale_f32 v6, vcc, s10, v3, s10
	v_mul_f32_e32 v7, v6, v5
	v_fma_f32 v8, -v4, v7, v6
	v_fmac_f32_e32 v7, v8, v5
	v_fma_f32 v4, -v4, v7, v6
	v_div_fmas_f32 v4, v4, v5, v7
	v_div_fixup_f32 v3, v4, v3, s10
	v_mul_f32_e32 v4, v3, v1
	v_mul_f32_e32 v5, v3, v2
	v_mov_b32_e32 v6, v155
	v_cvt_pk_fp8_f32 v6, v4, v5
	v_cvt_pk_f32_fp8_e32 v[4:5], v6
	v_fma_f32 v1, v3, v1, -v4
	v_fma_f32 v2, v3, v2, -v5
	v_mov_b32_e32 v4, v155
	v_cvt_pk_fp8_f32 v4, v1, v2
	ds_read2st64_b32 v[2:3], v178 offset0:36 offset1:37
	v_lshlrev_b32_e32 v1, 16, v6
	v_and_b32_e32 v1, 0xff0000, v1
	v_lshlrev_b32_e32 v5, 24, v4
	v_lshlrev_b32_e32 v4, 16, v4
	s_waitcnt lgkmcnt(0)
	v_or3_b32 v1, v2, v1, v5
	v_lshlrev_b32_e32 v2, 8, v6
	v_perm_b32 v2, v4, v2, s0
	v_or_b32_e32 v2, v2, v3
	ds_write2st64_b32 v178, v1, v2 offset0:38 offset1:39
	ds_read2st64_b32 v[2:3], v178 offset0:44 offset1:45
	ds_read2st64_b32 v[4:5], v178 offset0:46 offset1:47
	s_mov_b32 s0, 0x3e6d3388
	s_waitcnt lgkmcnt(0)
	v_fma_f32 v1, |v4|, s0, 1.0
	v_rcp_f32_e32 v1, v1
	v_cmp_gt_f32_e32 vcc, 0, v4
	v_fmamk_f32 v6, v1, 0x3f07dc22, v210
	v_fmaak_f32 v6, v1, v6, 0x3f35f0e3
	v_fmaak_f32 v6, v1, v6, 0xbe11a98e
	v_fmaak_f32 v6, v1, v6, 0x3e027906
	v_mul_f32_e32 v1, v1, v6
	v_mul_f32_e32 v6, v4, v4
	v_mul_f32_e32 v6, 0xbf38aa3b, v6
	v_exp_f32_e32 v6, v6
	s_nop 0
	v_mul_f32_e32 v1, v6, v1
	v_mul_f32_e32 v6, v4, v1
	v_fma_f32 v1, -v4, v1, v4
	v_cndmask_b32_e32 v1, v1, v6, vcc
	v_mul_f32_e32 v1, v2, v1
	v_fma_f32 v2, |v5|, s0, 1.0
	v_rcp_f32_e32 v2, v2
	v_cmp_gt_f32_e32 vcc, 0, v5
	v_fmamk_f32 v4, v2, 0x3f07dc22, v210
	v_fmaak_f32 v4, v2, v4, 0x3f35f0e3
	v_fmaak_f32 v4, v2, v4, 0xbe11a98e
	v_fmaak_f32 v4, v2, v4, 0x3e027906
	v_mul_f32_e32 v2, v2, v4
	v_mul_f32_e32 v4, v5, v5
	v_mul_f32_e32 v4, 0xbf38aa3b, v4
	v_exp_f32_e32 v4, v4
	s_nop 0
	v_mul_f32_e32 v2, v4, v2
	v_mul_f32_e32 v4, v5, v2
	v_fma_f32 v2, -v5, v2, v5
	v_cndmask_b32_e32 v2, v2, v4, vcc
	v_mul_f32_e32 v2, v3, v2
	v_max_f32_e64 v3, |v1|, |v2|
	s_nop 1
	v_mov_b32_dpp v4, v3 quad_perm:[1,0,3,2] row_mask:0xf bank_mask:0xf bound_ctrl:1
	v_max_f32_e32 v4, v4, v4
	v_max_f32_e32 v3, v3, v4
	s_nop 1
	v_mov_b32_dpp v4, v3 quad_perm:[2,3,0,1] row_mask:0xf bank_mask:0xf bound_ctrl:1
	v_max_f32_e32 v4, v4, v4
	v_max_f32_e32 v3, v3, v4
	s_nop 1
	v_mov_b32_dpp v4, v3 row_half_mirror row_mask:0xf bank_mask:0xf bound_ctrl:1
	v_max_f32_e32 v4, v4, v4
	v_max_f32_e32 v3, v3, v4
	s_nop 1
	v_mov_b32_dpp v4, v3 row_mirror row_mask:0xf bank_mask:0xf bound_ctrl:1
	v_max_f32_e32 v4, v4, v4
	v_max_f32_e32 v3, v3, v4
	s_nop 0
	v_readlane_b32 s0, v3, 0
	v_readlane_b32 s1, v3, 16
	v_readlane_b32 s10, v3, 32
	v_readlane_b32 s11, v3, 48
	v_max_f32_e64 v3, s1, s1
	v_max_f32_e64 v4, s0, s0
	v_max_f32_e32 v3, v4, v3
	v_max_f32_e64 v4, s11, s11
	v_max_f32_e64 v5, s10, s10
	v_max_f32_e32 v4, v5, v4
	s_mov_b32 s0, 0xda24260
	v_max3_f32 v3, v3, v4, s0
	s_mov_b64 s[0:1], exec
	v_readlane_b32 s10, v254, 21
	v_readlane_b32 s11, v254, 22
	s_and_b64 s[10:11], s[0:1], s[10:11]
	s_mov_b64 exec, s[10:11]
	v_mul_f32_e32 v4, 0x3b888889, v3
	v_mov_b32_e32 v5, s93
	ds_write_b32 v5, v4 offset:14364
	s_or_b64 exec, exec, s[0:1]
	s_mov_b32 s10, 0x43700000
	v_div_scale_f32 v4, s[0:1], v3, v3, s10
	v_rcp_f32_e32 v5, v4
	s_mov_b32 s0, 0x7020c0c
	v_readlane_b32 s12, v254, 29
	v_fma_f32 v6, -v4, v5, 1.0
	v_fmac_f32_e32 v5, v6, v5
	v_div_scale_f32 v6, vcc, s10, v3, s10
	v_mul_f32_e32 v7, v6, v5
	v_fma_f32 v8, -v4, v7, v6
	v_fmac_f32_e32 v7, v8, v5
	v_fma_f32 v4, -v4, v7, v6
	v_div_fmas_f32 v4, v4, v5, v7
	v_div_fixup_f32 v3, v4, v3, s10
	v_mul_f32_e32 v4, v3, v1
	v_mul_f32_e32 v5, v3, v2
	v_mov_b32_e32 v6, v155
	v_cvt_pk_fp8_f32 v6, v4, v5
	s_mov_b32 s10, 0
	v_cvt_pk_f32_fp8_e32 v[4:5], v6
	v_fma_f32 v1, v3, v1, -v4
	v_fma_f32 v2, v3, v2, -v5
	v_mov_b32_e32 v4, v155
	v_cvt_pk_fp8_f32 v4, v1, v2
	ds_read2st64_b32 v[2:3], v178 offset0:42 offset1:43
	v_lshlrev_b32_e32 v1, 16, v6
	v_and_b32_e32 v1, 0xff0000, v1
	v_lshlrev_b32_e32 v5, 24, v4
	v_lshlrev_b32_e32 v4, 16, v4
	s_waitcnt lgkmcnt(0)
	v_or3_b32 v1, v2, v1, v5
	v_lshlrev_b32_e32 v2, 8, v6
	v_perm_b32 v2, v4, v2, s0
	s_add_i32 s0, s40, 0xffffe000
	s_lshr_b32 s0, s0, 12
	s_add_i32 s0, s0, 1
	s_cmpk_gt_i32 s40, 0x1fff
	s_cselect_b32 s11, s0, 0
	v_readlane_b32 s0, v254, 20
	s_mul_i32 s0, s0, 3
	s_add_i32 s11, s11, s0
	v_or_b32_e32 v2, v2, v3
	s_mul_i32 s1, s11, 0x6000
	ds_write2st64_b32 v178, v1, v2 offset0:44 offset1:45
	s_mul_hi_u32 s0, s11, 0x6000
	s_add_u32 s1, s12, s1
	v_readlane_b32 s12, v254, 30
	s_waitcnt lgkmcnt(0)
	s_addc_u32 s12, s12, s0
	s_add_u32 s0, s1, 0x5000
	s_addc_u32 s1, s12, 0
